# SSD: batched LDS reads for decay factors, y-store waits relaxed, waves 4-7 run state update first, scan before fill; dt softplus loop 4 loads in flight
# speedup vs baseline: 1.0040x; 1.0040x over previous
; #define LAS __attribute__((address_space(3)))
; #define INP(k) inp_(a.in[k])
; __device__ __forceinline__ void phase_C1(const Args& a, unsigned char* ws, const int bid, int l, LAS unsigned char* lds, int tid, int wave, int lane) {
;     ...
;         const int combo = (item & 7) * 8 + (item >> 5), hq = (item >> 3) & 3;
;         const int b = combo >> 4, g = (combo >> 1) & 7, dir = combo & 1, h = 4 * g + hq;
;         const float Acoef = -__expf(INP(12)[l * 64 + dir * 32 + h]);
;         const float dskip = INP(13)[l * 32 + h];
;         f32x4 Hacc[4];
; #pragma unroll
;         for (int j = 0; j < 4; ++j) Hacc[j] = (f32x4){0.f, 0.f, 0.f, 0.f};
;         for (int i = tid; i < 17408 / 4; i += 512) ((LAS unsigned*)L_H)[i] = 0u;
;         u32x4 pc[4], pb[4], px[2]; float pd0 = 0.f, pd1 = 0.f;
;     ...
;         SSD_ISSUE(0);
; #pragma unroll 1
;         for (int step = 0; step < 66; ++step) {
.LBB0_95:
	s_cmp_lg_u32 s4, 0
	s_cselect_b64 s[70:71], -1, 0
	s_lshl_b32 s5, s46, 6
	s_add_i32 s0, s5, 0x49
	v_writelane_b32 v255, s0, 55
	s_lshl_b32 s94, s46, 1
	s_or_b32 s0, s5, 6
	s_or_b32 s3, s94, 1
	v_writelane_b32 v255, s0, 56
	s_lshl_b32 s0, s45, 2
	v_readlane_b32 s42, v254, 62
	v_readlane_b32 s43, v254, 63
	s_add_u32 s0, s42, s0
	s_addc_u32 s38, s43, 0
	s_lshl_b32 s42, s44, 2
	s_add_u32 s88, s0, s42
	s_addc_u32 s89, s38, 0
	s_lshl_b32 s0, s4, 12
	v_readlane_b32 s38, v254, 60
	s_add_u32 s0, s38, s0
	v_readlane_b32 s38, v254, 61
	s_addc_u32 s43, s38, 0
	s_lshl_b32 s38, s47, 1
	s_add_u32 s42, s0, s38
	s_addc_u32 s43, s43, 0
	v_lshl_add_u64 v[114:115], s[42:43], 0, v[160:161]
	v_readlane_b32 s42, v255, 8
	s_waitcnt vmcnt(11)
	v_mul_f32_e32 v41, 0x3fb8aa3b, v41
	v_readlane_b32 s43, v255, 9
	v_exp_f32_e32 v166, v41
	s_cmp_eq_u32 s4, 0
	v_cndmask_b32_e64 v41, 0, 1, s[42:43]
	v_readlane_b32 s42, v255, 6
	v_readlane_b32 s43, v255, 7
	v_readlane_b32 s44, v255, 12
	v_readlane_b32 s45, v255, 13
	v_cndmask_b32_e64 v42, 0, 1, s[42:43]
	s_cselect_b64 s[42:43], -1, 0
	v_cndmask_b32_e64 v41, v41, v42, s[42:43]
	v_cndmask_b32_e64 v42, 0, 1, s[44:45]
	v_readlane_b32 s44, v255, 10
	v_readlane_b32 s45, v255, 11
	v_and_b32_e32 v41, 1, v41
	v_readlane_b32 s60, v255, 38
	v_cndmask_b32_e64 v43, 0, 1, s[44:45]
	v_readlane_b32 s44, v255, 16
	v_readlane_b32 s45, v255, 17
	v_cndmask_b32_e64 v42, v42, v43, s[42:43]
	v_readlane_b32 s61, v255, 39
	v_cndmask_b32_e64 v43, 0, 1, s[44:45]
	v_readlane_b32 s44, v255, 14
	v_readlane_b32 s45, v255, 15
	v_readlane_b32 s62, v255, 42
	v_readlane_b32 s63, v255, 43
	v_cndmask_b32_e64 v44, 0, 1, s[44:45]
	v_readlane_b32 s44, v255, 20
	v_readlane_b32 s45, v255, 21
	v_cndmask_b32_e64 v43, v43, v44, s[42:43]
	v_readlane_b32 s64, v255, 46
	v_cndmask_b32_e64 v44, 0, 1, s[44:45]
	v_readlane_b32 s44, v255, 18
	v_readlane_b32 s45, v255, 19
	v_readlane_b32 s65, v255, 47
	v_readlane_b32 s66, v255, 50
	v_cndmask_b32_e64 v45, 0, 1, s[44:45]
	v_readlane_b32 s44, v255, 24
	v_readlane_b32 s45, v255, 25
	v_cndmask_b32_e64 v44, v44, v45, s[42:43]
	v_readlane_b32 s67, v255, 51
	v_cndmask_b32_e64 v45, 0, 1, s[44:45]
	v_readlane_b32 s44, v255, 22
	v_readlane_b32 s45, v255, 23
	s_mov_b32 s74, 0
	s_waitcnt vmcnt(10)
	v_mov_b32_e32 v111, v110
	v_cndmask_b32_e64 v46, 0, 1, s[44:45]
	v_readlane_b32 s44, v255, 28
	v_readlane_b32 s45, v255, 29
	v_cndmask_b32_e64 v45, v45, v46, s[42:43]
	s_movk_i32 s4, 0x48
	v_cndmask_b32_e64 v46, 0, 1, s[44:45]
	v_readlane_b32 s44, v255, 26
	v_readlane_b32 s45, v255, 27
	s_lshl_b32 s95, s1, 1
	s_mov_b32 s72, 0
	v_cndmask_b32_e64 v47, 0, 1, s[44:45]
	v_readlane_b32 s44, v255, 32
	v_readlane_b32 s45, v255, 33
	v_cndmask_b32_e64 v46, v46, v47, s[42:43]
	v_mov_b32_e32 v50, v40
	v_cndmask_b32_e64 v47, 0, 1, s[44:45]
	v_readlane_b32 s44, v255, 30
	v_readlane_b32 s45, v255, 31
	v_mov_b32_e32 v51, v40
	v_mov_b32_e32 v52, v40
	v_cndmask_b32_e64 v48, 0, 1, s[44:45]
	v_readlane_b32 s44, v255, 36
	v_readlane_b32 s45, v255, 37
	v_cndmask_b32_e64 v47, v47, v48, s[42:43]
	v_mov_b32_e32 v53, v40
	v_cndmask_b32_e64 v48, 0, 1, s[44:45]
	v_readlane_b32 s44, v255, 34
	v_readlane_b32 s45, v255, 35
	v_mov_b32_e32 v54, v40
	v_mov_b32_e32 v55, v40
	v_cndmask_b32_e64 v49, 0, 1, s[44:45]
	v_cmp_eq_u32_e64 s[44:45], 1, v41
	v_and_b32_e32 v41, 1, v42
	v_cmp_eq_u32_e64 s[46:47], 1, v41
	v_and_b32_e32 v41, 1, v43
	v_cmp_eq_u32_e64 s[48:49], 1, v41
	v_and_b32_e32 v41, 1, v44
	v_cmp_eq_u32_e64 s[50:51], 1, v41
	v_and_b32_e32 v41, 1, v45
	v_cmp_eq_u32_e64 s[52:53], 1, v41
	v_and_b32_e32 v41, 1, v46
	v_cndmask_b32_e64 v48, v48, v49, s[42:43]
	v_cmp_eq_u32_e64 s[54:55], 1, v41
	v_and_b32_e32 v41, 1, v47
	v_cmp_eq_u32_e64 s[56:57], 1, v41
	v_and_b32_e32 v41, 1, v48
	v_cmp_eq_u32_e64 s[58:59], 1, v41
	v_cndmask_b32_e64 v41, 0, 1, s[60:61]
	v_readlane_b32 s60, v255, 40
	v_readlane_b32 s61, v255, 41
	v_mov_b32_e32 v43, v40
	v_mov_b32_e32 v44, v40
	v_cndmask_b32_e64 v42, 0, 1, s[60:61]
	v_cndmask_b32_e64 v41, v42, v41, s[42:43]
	v_and_b32_e32 v41, 1, v41
	v_cmp_eq_u32_e64 s[60:61], 1, v41
	v_cndmask_b32_e64 v41, 0, 1, s[62:63]
	v_readlane_b32 s62, v255, 44
	v_readlane_b32 s63, v255, 45
	v_mov_b32_e32 v45, v40
	v_mov_b32_e32 v46, v40
	v_cndmask_b32_e64 v42, 0, 1, s[62:63]
	v_cndmask_b32_e64 v41, v42, v41, s[42:43]
	v_and_b32_e32 v41, 1, v41
	v_cmp_eq_u32_e64 s[62:63], 1, v41
	v_cndmask_b32_e64 v41, 0, 1, s[64:65]
	v_readlane_b32 s64, v255, 48
	v_readlane_b32 s65, v255, 49
	v_mov_b32_e32 v47, v40
	v_mov_b32_e32 v48, v40
	v_cndmask_b32_e64 v42, 0, 1, s[64:65]
	v_cndmask_b32_e64 v41, v42, v41, s[42:43]
	v_and_b32_e32 v41, 1, v41
	v_cmp_eq_u32_e64 s[64:65], 1, v41
	v_cndmask_b32_e64 v41, 0, 1, s[66:67]
	v_readlane_b32 s66, v255, 52
	v_readlane_b32 s67, v255, 53
	v_mov_b32_e32 v49, v40
	s_nop 0
	v_cndmask_b32_e64 v42, 0, 1, s[66:67]
	v_cndmask_b32_e64 v41, v42, v41, s[42:43]
	v_and_b32_e32 v41, 1, v41
	v_cmp_eq_u32_e64 s[66:67], 1, v41
	v_mov_b32_e32 v41, v40
	v_mov_b32_e32 v42, v40
	s_waitcnt vmcnt(0)
	s_branch .LBB0_97

; #define LAS __attribute__((address_space(3)))
; __device__ __forceinline__ void phase_C1(const Args& a, unsigned char* ws, const int bid, int l, LAS unsigned char* lds, int tid, int wave, int lane) {
;     ...
; #pragma unroll
;             for (int i = 0; i < 4; ++i) { *(LAS u32x4*)(L_C + wCB + i * 32 * 272) = pc[i]; *(LAS u32x4*)(L_B + wCB + i * 32 * 272) = pb[i]; }
; #pragma unroll
;             for (int i = 0; i < 2; ++i) *(LAS u32x4*)(L_X + wX + i * 64 * 144) = px[i];
;             if (wave == 0) {
;                 const int t0 = 2 * lane;
;                 const float d0 = pd0, d1 = pd1;
;                 const float a0 = d0 * Acoef, a1 = d1 * Acoef, pair = a0 + a1; const float incl = wave_incl_scan(pair);
;                 const float tot = __builtin_bit_cast(float, __builtin_amdgcn_readlane(__builtin_bit_cast(int, incl), 63)), excl = incl - pair;
;                 float c0v, c1v, ref;
;                 if (dir == 0) { c0v = excl + a0; c1v = incl; ref = __shfl(c1v, (lane & ~7) + 7); }
;                 else { c0v = tot - excl; c1v = tot - incl + a1; ref = __shfl(c0v, lane & ~7); }
;                 cs[t0] = c0v; cs[t0 + 1] = c1v; dtv[t0] = d0; dtv[t0 + 1] = d1;
;                 wgt[t0] = d0 * __expf(tot - c0v); wgt[t0 + 1] = d1 * __expf(tot - c1v);
;                 ecs[t0] = __expf(c0v); ecs[t0 + 1] = __expf(c1v);
;                 f2dt[t0] = d0 * __expf(ref - c0v); f2dt[t0 + 1] = d1 * __expf(ref - c1v);
;                 if ((lane & 7) == 0) refarr[lane >> 3] = ref;
;                 if (lane == 0) totp[0] = tot;
;             }
.LBB0_108:
	v_cndmask_b32_e64 v56, 0, 1, s[24:25]
	v_cmp_ne_u32_e64 s[0:1], 1, v56
	s_andn2_b64 vcc, exec, s[24:25]
	s_cbranch_vccnz .Lssd_ladder
	s_waitcnt vmcnt(2)
	v_mul_f32_e64 v56, v113, -v166
	v_fma_f32 v58, v112, -v166, v56
	v_mov_b32_e32 v59, v161
	s_mov_b64 s[90:91], -1
	v_add_f32_dpp v57, v58, v58 row_shr:1 row_mask:0xf bank_mask:0xf bound_ctrl:1
	s_and_b64 vcc, exec, s[70:71]
	s_nop 0
	v_add_f32_dpp v57, v57, v57 row_shr:2 row_mask:0xf bank_mask:0xf bound_ctrl:1
	s_nop 1
	v_add_f32_dpp v57, v57, v57 row_shr:4 row_mask:0xf bank_mask:0xf bound_ctrl:1
	s_nop 1
	v_add_f32_dpp v57, v57, v57 row_shr:8 row_mask:0xf bank_mask:0xf bound_ctrl:1
	s_nop 1
	v_mov_b32_dpp v59, v57 row_bcast:15 row_mask:0xa bank_mask:0xf bound_ctrl:1
	v_add_f32_e32 v57, v57, v59
	v_mov_b32_e32 v59, v161
	s_nop 1
	v_mov_b32_dpp v59, v57 row_bcast:31 row_mask:0xc bank_mask:0xf bound_ctrl:1
	v_add_f32_e32 v57, v57, v59
	v_sub_f32_e32 v63, v57, v58
	v_readlane_b32 s74, v57, 63
	s_cbranch_vccz .LBB0_111
	s_nop 0
	v_sub_f32_e32 v59, s74, v57
	v_sub_f32_e32 v58, s74, v63
	v_add_f32_e32 v59, v56, v59
	ds_bpermute_b32 v62, v159, v58
	s_mov_b64 s[90:91], 0
	v_mov_b32_e32 v56, v58
	v_mov_b64_e32 v[60:61], v[58:59]

; #define LAS __attribute__((address_space(3)))
; __device__ __forceinline__ void phase_C1(const Args& a, unsigned char* ws, const int bid, int l, LAS unsigned char* lds, int tid, int wave, int lane) {
;     ...
; #pragma unroll
;             for (int i = 0; i < 4; ++i) { *(LAS u32x4*)(L_C + wCB + i * 32 * 272) = pc[i]; *(LAS u32x4*)(L_B + wCB + i * 32 * 272) = pb[i]; }
; #pragma unroll
;             for (int i = 0; i < 2; ++i) *(LAS u32x4*)(L_X + wX + i * 64 * 144) = px[i];
.Lssd_ladder:
	s_waitcnt vmcnt(11)
	ds_write_b128 v144, v[0:3]
	s_waitcnt vmcnt(10)
	ds_write_b128 v144, v[4:7] offset:34816
	s_waitcnt vmcnt(9)
	ds_write_b128 v144, v[8:11] offset:8704
	s_waitcnt vmcnt(8)
	ds_write_b128 v144, v[12:15] offset:43520
	s_waitcnt vmcnt(7)
	ds_write_b128 v144, v[16:19] offset:17408
	s_waitcnt vmcnt(6)
	ds_write_b128 v144, v[20:23] offset:52224
	s_waitcnt vmcnt(5)
	ds_write_b128 v144, v[24:27] offset:26112
	s_waitcnt vmcnt(4)
	ds_write_b128 v144, v[28:31] offset:60928
	s_waitcnt vmcnt(3)
	ds_write_b128 v145, v[32:35]
	s_waitcnt vmcnt(2)
	ds_write_b128 v145, v[36:39] offset:9216

; #define MFMA16(a, b, c) __builtin_amdgcn_mfma_f32_16x16x32_bf16((a), (b), (c), 0, 0, 0)
; __device__ __forceinline__ void phase_C1(const Args& a, unsigned char* ws, const int bid, int l, LAS unsigned char* lds, int tid, int wave, int lane) {
;     ...
;             {
;                 bf16x8 cqv[2], bq[2][4], hq[2][2];
;     ...
;                 SSD_LDH(0, 0);
; #pragma unroll
;                 for (int h2 = 0; h2 < 8; ++h2) { const int cb = h2 & 1, s_ = h2 >> 1, hf_ = h2 & 1;
;                     if (h2 < 7) SSD_LDH(cb ^ 1, h2 + 1);
;                     __builtin_amdgcn_sched_barrier(0);
; #pragma unroll
;                     for (int k = 0; k < 4; ++k) accA[4 * hf_ + k] = MFMA16(bq[cb][k], cqv[s_ & 1], accA[4 * hf_ + k]);
; #pragma unroll
;                     for (int p = 0; p < 2; ++p) accC[2 * hf_ + p] = MFMA16(hq[cb][p], cqv[s_ & 1], accC[2 * hf_ + p]);
;                     __builtin_amdgcn_sched_barrier(0); }
.LBB0_121:
	v_readfirstlane_b32 vcc_lo, v164
	s_nop 3
	s_cmp_lt_u32 vcc_lo, 0x100
	s_cbranch_scc0 .Lssd_alt_order
	v_add_u32_e32 v116, s33, v118
	ds_read_b128 v[56:59], v118 offset:34816
	ds_read_b128 v[60:63], v118 offset:39168
	ds_read_b128 v[64:67], v118 offset:43520
	ds_read_b128 v[68:71], v118 offset:47872
	ds_read_b128 v[72:75], v116
	ds_read_b128 v[76:79], v147
	ds_read_b128 v[80:83], v118 offset:52224
	ds_read_b128 v[84:87], v118 offset:56576
	ds_read_b128 v[88:91], v118 offset:60928
	ds_read_b128 v[92:95], v118 offset:65280
	ds_read_b128 v[96:99], v147 offset:1088
	ds_read_b128 v[100:103], v147 offset:8704
	ds_read_b128 v[168:171], v147 offset:9792
	s_waitcnt lgkmcnt(8)
	v_mfma_f32_16x16x32_bf16 v[56:59], v[56:59], v[72:75], 0
	v_mfma_f32_16x16x32_bf16 v[60:63], v[60:63], v[72:75], 0
	v_mfma_f32_16x16x32_bf16 v[64:67], v[64:67], v[72:75], 0
	v_mfma_f32_16x16x32_bf16 v[68:71], v[68:71], v[72:75], 0
	s_waitcnt lgkmcnt(7)
	v_mfma_f32_16x16x32_bf16 v[76:79], v[76:79], v[72:75], 0
	s_waitcnt lgkmcnt(2)
	v_mfma_f32_16x16x32_bf16 v[96:99], v[96:99], v[72:75], 0
	ds_read_b128 v[172:175], v118 offset:34880
	ds_read_b128 v[176:179], v118 offset:39232
	ds_read_b128 v[180:183], v118 offset:43584
	ds_read_b128 v[184:187], v118 offset:47936
	ds_read_b128 v[188:191], v116 offset:64
	ds_read_b128 v[212:215], v147 offset:64
	ds_read_b128 v[216:219], v147 offset:1152
	v_mfma_f32_16x16x32_bf16 v[80:83], v[80:83], v[72:75], 0
	v_mfma_f32_16x16x32_bf16 v[84:87], v[84:87], v[72:75], 0
	v_mfma_f32_16x16x32_bf16 v[88:91], v[88:91], v[72:75], 0
	v_mfma_f32_16x16x32_bf16 v[92:95], v[92:95], v[72:75], 0
	s_waitcnt lgkmcnt(8)
	v_mfma_f32_16x16x32_bf16 v[100:103], v[100:103], v[72:75], 0
	s_waitcnt lgkmcnt(7)
	v_mfma_f32_16x16x32_bf16 v[72:75], v[168:171], v[72:75], 0
	ds_read_b128 v[168:171], v118 offset:52288
	ds_read_b128 v[220:223], v118 offset:56640
	ds_read_b128 v[224:227], v118 offset:60992
	ds_read_b128 v[228:231], v118 offset:65344
	ds_read_b128 v[232:235], v147 offset:8768
	ds_read_b128 v[236:239], v147 offset:9856
	s_waitcnt lgkmcnt(8)
	v_mfma_f32_16x16x32_bf16 v[56:59], v[172:175], v[188:191], v[56:59]
	v_mfma_f32_16x16x32_bf16 v[60:63], v[176:179], v[188:191], v[60:63]
	v_mfma_f32_16x16x32_bf16 v[64:67], v[180:183], v[188:191], v[64:67]
	v_mfma_f32_16x16x32_bf16 v[68:71], v[184:187], v[188:191], v[68:71]
	s_waitcnt lgkmcnt(7)
	v_mfma_f32_16x16x32_bf16 v[76:79], v[212:215], v[188:191], v[76:79]
	s_waitcnt lgkmcnt(6)
	v_mfma_f32_16x16x32_bf16 v[96:99], v[216:219], v[188:191], v[96:99]
	ds_read_b128 v[172:175], v118 offset:34944
	ds_read_b128 v[176:179], v118 offset:39296
	ds_read_b128 v[180:183], v118 offset:43648
	ds_read_b128 v[184:187], v118 offset:48000
	ds_read_b128 v[212:215], v116 offset:128
	ds_read_b128 v[216:219], v147 offset:128
	ds_read_b128 v[240:243], v147 offset:1216
	s_waitcnt lgkmcnt(12)
	v_mfma_f32_16x16x32_bf16 v[80:83], v[168:171], v[188:191], v[80:83]
	s_waitcnt lgkmcnt(11)
	v_mfma_f32_16x16x32_bf16 v[84:87], v[220:223], v[188:191], v[84:87]
	s_waitcnt lgkmcnt(10)
	v_mfma_f32_16x16x32_bf16 v[88:91], v[224:227], v[188:191], v[88:91]
	s_waitcnt lgkmcnt(9)
	v_mfma_f32_16x16x32_bf16 v[92:95], v[228:231], v[188:191], v[92:95]
	s_waitcnt lgkmcnt(8)
	v_mfma_f32_16x16x32_bf16 v[100:103], v[232:235], v[188:191], v[100:103]
	s_waitcnt lgkmcnt(7)
	v_mfma_f32_16x16x32_bf16 v[72:75], v[236:239], v[188:191], v[72:75]
	ds_read_b128 v[168:171], v118 offset:52352
	ds_read_b128 v[188:191], v118 offset:56704
	ds_read_b128 v[220:223], v118 offset:61056
	ds_read_b128 v[224:227], v118 offset:65408
	ds_read_b128 v[228:231], v147 offset:8832
	ds_read_b128 v[232:235], v147 offset:9920
	s_waitcnt lgkmcnt(8)
	v_mfma_f32_16x16x32_bf16 v[56:59], v[172:175], v[212:215], v[56:59]
	v_mfma_f32_16x16x32_bf16 v[60:63], v[176:179], v[212:215], v[60:63]
	v_mfma_f32_16x16x32_bf16 v[64:67], v[180:183], v[212:215], v[64:67]
	v_mfma_f32_16x16x32_bf16 v[68:71], v[184:187], v[212:215], v[68:71]
	s_waitcnt lgkmcnt(7)
	v_mfma_f32_16x16x32_bf16 v[76:79], v[216:219], v[212:215], v[76:79]
	s_waitcnt lgkmcnt(6)
	v_mfma_f32_16x16x32_bf16 v[172:175], v[240:243], v[212:215], v[96:99]
	s_nop 2
	ds_read_b128 v[96:99], v118 offset:35008
	ds_read_b128 v[176:179], v118 offset:39360
	ds_read_b128 v[180:183], v118 offset:43712
	ds_read_b128 v[184:187], v118 offset:48064
	ds_read_b128 v[216:219], v116 offset:192
	ds_read_b128 v[236:239], v147 offset:192
	ds_read_b128 v[240:243], v147 offset:1280
	s_waitcnt lgkmcnt(12)
	v_mfma_f32_16x16x32_bf16 v[168:171], v[168:171], v[212:215], v[80:83]
	s_waitcnt lgkmcnt(11)
	v_mfma_f32_16x16x32_bf16 v[84:87], v[188:191], v[212:215], v[84:87]
	s_waitcnt lgkmcnt(10)
	v_mfma_f32_16x16x32_bf16 v[188:191], v[220:223], v[212:215], v[88:91]
	s_waitcnt lgkmcnt(9)
	v_mfma_f32_16x16x32_bf16 v[220:223], v[224:227], v[212:215], v[92:95]
	s_waitcnt lgkmcnt(8)
	v_mfma_f32_16x16x32_bf16 v[224:227], v[228:231], v[212:215], v[100:103]
	s_waitcnt lgkmcnt(7)
	v_mfma_f32_16x16x32_bf16 v[212:215], v[232:235], v[212:215], v[72:75]
	s_nop 2
	ds_read_b128 v[72:75], v118 offset:52416
	ds_read_b128 v[228:231], v118 offset:56768
	ds_read_b128 v[232:235], v118 offset:61120
	ds_read_b128 v[244:247], v118 offset:65472
	ds_read_b128 v[248:251], v147 offset:8896
	ds_read_b128 v[192:195], v147 offset:9984
	s_waitcnt lgkmcnt(8)
	v_mfma_f32_16x16x32_bf16 v[100:103], v[96:99], v[216:219], v[56:59]
	v_mfma_f32_16x16x32_bf16 v[96:99], v[176:179], v[216:219], v[60:63]
	v_mfma_f32_16x16x32_bf16 v[88:91], v[180:183], v[216:219], v[64:67]
	v_mfma_f32_16x16x32_bf16 v[80:83], v[184:187], v[216:219], v[68:71]
	s_waitcnt lgkmcnt(7)
	v_mfma_f32_16x16x32_bf16 v[68:71], v[236:239], v[216:219], v[76:79]
	s_waitcnt lgkmcnt(6)
; #define LAS __attribute__((address_space(3)))
; __device__ __forceinline__ unsigned cvt_pk_bf16(float lo, float hi) { unsigned r; asm volatile("v_cvt_pk_bf16_f32 %0, %1, %2" : "=v"(r) : "v"(lo), "v"(hi)); return r; }
; #define MFMA16(a, b, c) __builtin_amdgcn_mfma_f32_16x16x32_bf16((a), (b), (c), 0, 0, 0)
; #define TRB(base, krow0, col0, t) __builtin_amdgcn_ds_read_tr16_b64_v4i16((LAS s16x4*)((base) + trB + ((krow0) + 4 * (t)) * 272 + (col0) * 2))
; __device__ __forceinline__ void phase_C1(const Args& a, unsigned char* ws, const int bid, int l, LAS unsigned char* lds, int tid, int wave, int lane) {
;     ...
;             { const float etot = __expf(totp[0]);
; #pragma unroll
;               for (int j = 0; j < 4; ++j) Hacc[j] = Hacc[j] * etot;
; #pragma unroll
;               for (int s = 0; s < 4; ++s) { const s16x4 xlo = TRX(L_X, 32 * s, 16 * wr, 0), xhi = TRX(L_X, 32 * s, 16 * wr, 1);
;                   const f32x4 w0 = *(const LAS f32x4*)(wgt + s * 32 + fq * 8), w1 = *(const LAS f32x4*)(wgt + s * 32 + fq * 8 + 4);
;                   s16x4 blo[4], bhi[4];
; #pragma unroll
;                   for (int j = 0; j < 4; ++j) { blo[j] = TRB(L_B, 32 * s, 16 * (4 * wc + j), 0); bhi[j] = TRB(L_B, 32 * s, 16 * (4 * wc + j), 1); }
;                   __builtin_amdgcn_sched_barrier(0);
;                   const u32x2 xl = __builtin_bit_cast(u32x2, xlo), xh = __builtin_bit_cast(u32x2, xhi);
;                   u32x4 xs; xs.x = cvt_pk_bf16(bflo(xl.x) * w0.x, bfhi(xl.x) * w0.y); xs.y = cvt_pk_bf16(bflo(xl.y) * w0.z, bfhi(xl.y) * w0.w);
;                   xs.z = cvt_pk_bf16(bflo(xh.x) * w1.x, bfhi(xh.x) * w1.y); xs.w = cvt_pk_bf16(bflo(xh.y) * w1.z, bfhi(xh.y) * w1.w);
;                   const bf16x8 xq = __builtin_bit_cast(bf16x8, xs);
; #pragma unroll
;                   for (int j = 0; j < 4; ++j) { const bf16x8 bt = (bf16x8){blo[j].x, blo[j].y, blo[j].z, blo[j].w, bhi[j].x, bhi[j].y, bhi[j].z, bhi[j].w};
;                       Hacc[j] = MFMA16(bt, xq, Hacc[j]); }
;                   __builtin_amdgcn_sched_barrier(0); } }
;     ...
;               for (int kt = 0; kt < 8; ++kt) { const int k0 = kt * 16 + fq * 4;
;                   const bool kept = dir == 0 ? (kt < qt) : (kt > qt);
;                   const float f1 = __expf(csq - refarr[kt]); const f32x4 f2 = *(const LAS f32x4*)(f2dt + k0);
	v_mfma_f32_16x16x32_bf16 v[64:67], v[240:243], v[216:219], v[172:175]
	s_waitcnt lgkmcnt(5)
	v_mfma_f32_16x16x32_bf16 v[92:95], v[72:75], v[216:219], v[168:171]
	s_waitcnt lgkmcnt(4)
	v_mfma_f32_16x16x32_bf16 v[84:87], v[228:231], v[216:219], v[84:87]
	s_waitcnt lgkmcnt(3)
	v_mfma_f32_16x16x32_bf16 v[76:79], v[232:235], v[216:219], v[188:191]
	s_waitcnt lgkmcnt(2)
	v_mfma_f32_16x16x32_bf16 v[72:75], v[244:247], v[216:219], v[220:223]
	s_waitcnt lgkmcnt(1)
	v_mfma_f32_16x16x32_bf16 v[60:63], v[248:251], v[216:219], v[224:227]
	s_waitcnt lgkmcnt(0)
	v_mfma_f32_16x16x32_bf16 v[56:59], v[192:195], v[216:219], v[212:215]
	v_mov_b32_e32 v116, 0x22e00
	ds_read_b128 v[244:247], v116
	ds_read_b128 v[248:251], v116 offset:16
	ds_read_b128 v[216:219], v133
	ds_read_b128 v[220:223], v134
	ds_read_b128 v[224:227], v135
	ds_read_b128 v[228:231], v136
	ds_read_b128 v[232:235], v137
	ds_read_b128 v[236:239], v138
	ds_read_b128 v[240:243], v139
	ds_read_b128 v[212:215], v132
	v_mov_b32_e32 v116, s87
	ds_read_b32 v116, v116
	s_waitcnt lgkmcnt(0)
	v_mul_f32_e32 v116, 0x3fb8aa3b, v116
	v_exp_f32_e32 v116, v116
	s_nop 0
	v_pk_mul_f32 v[42:43], v[42:43], v[116:117] op_sel_hi:[1,0]
	v_pk_mul_f32 v[40:41], v[40:41], v[116:117] op_sel_hi:[1,0]
	v_pk_mul_f32 v[46:47], v[46:47], v[116:117] op_sel_hi:[1,0]
	v_pk_mul_f32 v[44:45], v[44:45], v[116:117] op_sel_hi:[1,0]
	v_pk_mul_f32 v[50:51], v[50:51], v[116:117] op_sel_hi:[1,0]
	v_pk_mul_f32 v[48:49], v[48:49], v[116:117] op_sel_hi:[1,0]
	v_pk_mul_f32 v[54:55], v[54:55], v[116:117] op_sel_hi:[1,0]
	v_pk_mul_f32 v[52:53], v[52:53], v[116:117] op_sel_hi:[1,0]
	ds_read_b64_tr_b16 v[116:117], v140
	ds_read_b64_tr_b16 v[192:193], v140 offset:576
	ds_read_b128 v[168:171], v125
	ds_read_b128 v[172:175], v125 offset:16
	ds_read_b64_tr_b16 v[178:179], v141 offset:35904
	ds_read_b64_tr_b16 v[176:177], v141 offset:34816
	ds_read_b64_tr_b16 v[180:181], v141 offset:34848
	ds_read_b64_tr_b16 v[182:183], v141 offset:35936
	ds_read_b64_tr_b16 v[184:185], v141 offset:34880
	ds_read_b64_tr_b16 v[186:187], v141 offset:35968
	ds_read_b64_tr_b16 v[188:189], v141 offset:34912
	ds_read_b64_tr_b16 v[190:191], v141 offset:36000
	s_waitcnt lgkmcnt(11)
	v_lshlrev_b32_e32 v194, 16, v116
	v_and_b32_e32 v116, 0xffff0000, v116
	s_waitcnt lgkmcnt(9)
	v_mul_f32_e32 v168, v168, v194
	v_mul_f32_e32 v116, v169, v116
	v_cvt_pk_bf16_f32 v168, v168, v116
	v_lshlrev_b32_e32 v116, 16, v117
	v_and_b32_e32 v117, 0xffff0000, v117
	v_mul_f32_e32 v116, v170, v116
	v_mul_f32_e32 v117, v171, v117
	v_cvt_pk_bf16_f32 v169, v116, v117
	v_lshlrev_b32_e32 v116, 16, v192
	v_and_b32_e32 v117, 0xffff0000, v192
	s_waitcnt lgkmcnt(8)
	v_mul_f32_e32 v116, v172, v116
	v_mul_f32_e32 v117, v173, v117
	v_cvt_pk_bf16_f32 v170, v116, v117
	v_lshlrev_b32_e32 v116, 16, v193
	v_and_b32_e32 v117, 0xffff0000, v193
	v_mul_f32_e32 v116, v174, v116
	v_mul_f32_e32 v117, v175, v117
	v_cvt_pk_bf16_f32 v171, v116, v117
	s_waitcnt lgkmcnt(6)
	v_mfma_f32_16x16x32_bf16 v[40:43], v[176:179], v[168:171], v[40:43]
	s_waitcnt lgkmcnt(4)
	v_mfma_f32_16x16x32_bf16 v[44:47], v[180:183], v[168:171], v[44:47]
	s_waitcnt lgkmcnt(2)
	v_mfma_f32_16x16x32_bf16 v[48:51], v[184:187], v[168:171], v[48:51]
	s_waitcnt lgkmcnt(0)
	v_mfma_f32_16x16x32_bf16 v[52:55], v[188:191], v[168:171], v[52:55]
	ds_read_b128 v[168:171], v125 offset:128
	ds_read_b128 v[172:175], v125 offset:144
	ds_read_b64_tr_b16 v[116:117], v140 offset:4608
	ds_read_b64_tr_b16 v[192:193], v140 offset:5184
	ds_read_b64_tr_b16 v[176:177], v141 offset:43520
	ds_read_b64_tr_b16 v[180:181], v141 offset:43552
	ds_read_b64_tr_b16 v[178:179], v141 offset:44608
	ds_read_b64_tr_b16 v[182:183], v141 offset:44640
	ds_read_b64_tr_b16 v[184:185], v141 offset:43584
	ds_read_b64_tr_b16 v[188:189], v141 offset:43616
	ds_read_b64_tr_b16 v[186:187], v141 offset:44672
	ds_read_b64_tr_b16 v[190:191], v141 offset:44704
	s_waitcnt lgkmcnt(9)
	v_lshlrev_b32_e32 v194, 16, v116
	v_and_b32_e32 v116, 0xffff0000, v116
	v_mul_f32_e32 v168, v168, v194
	v_mul_f32_e32 v116, v169, v116
	v_cvt_pk_bf16_f32 v168, v168, v116
	v_lshlrev_b32_e32 v116, 16, v117
	v_and_b32_e32 v117, 0xffff0000, v117
	v_mul_f32_e32 v116, v170, v116
	v_mul_f32_e32 v117, v171, v117
	v_cvt_pk_bf16_f32 v169, v116, v117
	s_waitcnt lgkmcnt(8)
	v_lshlrev_b32_e32 v116, 16, v192
	v_and_b32_e32 v117, 0xffff0000, v192
	v_mul_f32_e32 v116, v172, v116
	v_mul_f32_e32 v117, v173, v117
	v_cvt_pk_bf16_f32 v170, v116, v117
	v_lshlrev_b32_e32 v116, 16, v193
	v_and_b32_e32 v117, 0xffff0000, v193
	v_mul_f32_e32 v116, v174, v116
	v_mul_f32_e32 v117, v175, v117
	v_cvt_pk_bf16_f32 v171, v116, v117
	s_waitcnt lgkmcnt(5)
	v_mfma_f32_16x16x32_bf16 v[40:43], v[176:179], v[168:171], v[40:43]
	s_waitcnt lgkmcnt(4)
	v_mfma_f32_16x16x32_bf16 v[44:47], v[180:183], v[168:171], v[44:47]
	s_waitcnt lgkmcnt(1)
	v_mfma_f32_16x16x32_bf16 v[48:51], v[184:187], v[168:171], v[48:51]
	s_waitcnt lgkmcnt(0)
	v_mfma_f32_16x16x32_bf16 v[52:55], v[188:191], v[168:171], v[52:55]
	ds_read_b128 v[168:171], v125 offset:256
	ds_read_b128 v[172:175], v125 offset:272
	ds_read_b64_tr_b16 v[116:117], v140 offset:9216
	ds_read_b64_tr_b16 v[192:193], v140 offset:9792
	ds_read_b64_tr_b16 v[176:177], v141 offset:52224
	ds_read_b64_tr_b16 v[180:181], v141 offset:52256
	ds_read_b64_tr_b16 v[178:179], v141 offset:53312
	ds_read_b64_tr_b16 v[182:183], v141 offset:53344
	ds_read_b64_tr_b16 v[184:185], v141 offset:52288
	ds_read_b64_tr_b16 v[188:189], v141 offset:52320
	ds_read_b64_tr_b16 v[186:187], v141 offset:53376
	ds_read_b64_tr_b16 v[190:191], v141 offset:53408
	s_waitcnt lgkmcnt(9)
; #define LAS __attribute__((address_space(3)))
; __device__ __forceinline__ unsigned cvt_pk_bf16(float lo, float hi) { unsigned r; asm volatile("v_cvt_pk_bf16_f32 %0, %1, %2" : "=v"(r) : "v"(lo), "v"(hi)); return r; }
; #define MFMA16(a, b, c) __builtin_amdgcn_mfma_f32_16x16x32_bf16((a), (b), (c), 0, 0, 0)
; #define TRB(base, krow0, col0, t) __builtin_amdgcn_ds_read_tr16_b64_v4i16((LAS s16x4*)((base) + trB + ((krow0) + 4 * (t)) * 272 + (col0) * 2))
; #define TRX(base, krow0, col0, t) __builtin_amdgcn_ds_read_tr16_b64_v4i16((LAS s16x4*)((base) + trX + ((krow0) + 4 * (t)) * 144 + (col0) * 2))
; __device__ __forceinline__ void phase_C1(const Args& a, unsigned char* ws, const int bid, int l, LAS unsigned char* lds, int tid, int wave, int lane) {
;     ...
;               for (int s = 0; s < 4; ++s) { const s16x4 xlo = TRX(L_X, 32 * s, 16 * wr, 0), xhi = TRX(L_X, 32 * s, 16 * wr, 1);
;                   const f32x4 w0 = *(const LAS f32x4*)(wgt + s * 32 + fq * 8), w1 = *(const LAS f32x4*)(wgt + s * 32 + fq * 8 + 4);
;                   s16x4 blo[4], bhi[4];
; #pragma unroll
;                   for (int j = 0; j < 4; ++j) { blo[j] = TRB(L_B, 32 * s, 16 * (4 * wc + j), 0); bhi[j] = TRB(L_B, 32 * s, 16 * (4 * wc + j), 1); }
;                   __builtin_amdgcn_sched_barrier(0);
;                   const u32x2 xl = __builtin_bit_cast(u32x2, xlo), xh = __builtin_bit_cast(u32x2, xhi);
;                   u32x4 xs; xs.x = cvt_pk_bf16(bflo(xl.x) * w0.x, bfhi(xl.x) * w0.y); xs.y = cvt_pk_bf16(bflo(xl.y) * w0.z, bfhi(xl.y) * w0.w);
;                   xs.z = cvt_pk_bf16(bflo(xh.x) * w1.x, bfhi(xh.x) * w1.y); xs.w = cvt_pk_bf16(bflo(xh.y) * w1.z, bfhi(xh.y) * w1.w);
;                   const bf16x8 xq = __builtin_bit_cast(bf16x8, xs);
; #pragma unroll
;                   for (int j = 0; j < 4; ++j) { const bf16x8 bt = (bf16x8){blo[j].x, blo[j].y, blo[j].z, blo[j].w, bhi[j].x, bhi[j].y, bhi[j].z, bhi[j].w};
;                       Hacc[j] = MFMA16(bt, xq, Hacc[j]); }
;                   __builtin_amdgcn_sched_barrier(0); } }
	v_lshlrev_b32_e32 v194, 16, v116
	v_and_b32_e32 v116, 0xffff0000, v116
	v_mul_f32_e32 v168, v168, v194
	v_mul_f32_e32 v116, v169, v116
	v_cvt_pk_bf16_f32 v168, v168, v116
	v_lshlrev_b32_e32 v116, 16, v117
	v_and_b32_e32 v117, 0xffff0000, v117
	v_mul_f32_e32 v116, v170, v116
	v_mul_f32_e32 v117, v171, v117
	v_cvt_pk_bf16_f32 v169, v116, v117
	s_waitcnt lgkmcnt(8)
	v_lshlrev_b32_e32 v116, 16, v192
	v_and_b32_e32 v117, 0xffff0000, v192
	v_mul_f32_e32 v116, v172, v116
	v_mul_f32_e32 v117, v173, v117
	v_cvt_pk_bf16_f32 v170, v116, v117
	v_lshlrev_b32_e32 v116, 16, v193
	v_and_b32_e32 v117, 0xffff0000, v193
	v_mul_f32_e32 v116, v174, v116
	v_mul_f32_e32 v117, v175, v117
	v_cvt_pk_bf16_f32 v171, v116, v117
	s_waitcnt lgkmcnt(5)
	v_mfma_f32_16x16x32_bf16 v[40:43], v[176:179], v[168:171], v[40:43]
	s_waitcnt lgkmcnt(4)
	v_mfma_f32_16x16x32_bf16 v[44:47], v[180:183], v[168:171], v[44:47]
	s_waitcnt lgkmcnt(1)
	v_mfma_f32_16x16x32_bf16 v[48:51], v[184:187], v[168:171], v[48:51]
	s_waitcnt lgkmcnt(0)
	v_mfma_f32_16x16x32_bf16 v[52:55], v[188:191], v[168:171], v[52:55]
	ds_read_b128 v[168:171], v125 offset:384
	ds_read_b128 v[172:175], v125 offset:400
	ds_read_b64_tr_b16 v[116:117], v140 offset:13824
	ds_read_b64_tr_b16 v[192:193], v140 offset:14400
	ds_read_b64_tr_b16 v[176:177], v141 offset:60928
	ds_read_b64_tr_b16 v[180:181], v141 offset:60960
	ds_read_b64_tr_b16 v[178:179], v141 offset:62016
	ds_read_b64_tr_b16 v[182:183], v141 offset:62048
	ds_read_b64_tr_b16 v[184:185], v141 offset:60992
	ds_read_b64_tr_b16 v[188:189], v141 offset:61024
	ds_read_b64_tr_b16 v[186:187], v141 offset:62080
	ds_read_b64_tr_b16 v[190:191], v141 offset:62112
	s_waitcnt lgkmcnt(9)
	v_lshlrev_b32_e32 v194, 16, v116
	v_and_b32_e32 v116, 0xffff0000, v116
	v_mul_f32_e32 v168, v168, v194
	v_mul_f32_e32 v116, v169, v116
	v_cvt_pk_bf16_f32 v168, v168, v116
	v_lshlrev_b32_e32 v116, 16, v117
	v_and_b32_e32 v117, 0xffff0000, v117
	v_mul_f32_e32 v116, v170, v116
	v_mul_f32_e32 v117, v171, v117
	v_cvt_pk_bf16_f32 v169, v116, v117
	s_waitcnt lgkmcnt(8)
	v_lshlrev_b32_e32 v116, 16, v192
	v_and_b32_e32 v117, 0xffff0000, v192
	v_mul_f32_e32 v116, v172, v116
	v_mul_f32_e32 v117, v173, v117
	v_cvt_pk_bf16_f32 v170, v116, v117
	v_lshlrev_b32_e32 v116, 16, v193
	v_and_b32_e32 v117, 0xffff0000, v193
	v_mul_f32_e32 v116, v174, v116
	v_mul_f32_e32 v117, v175, v117
	v_cvt_pk_bf16_f32 v171, v116, v117
	s_waitcnt lgkmcnt(5)
	v_mfma_f32_16x16x32_bf16 v[40:43], v[176:179], v[168:171], v[40:43]
	s_waitcnt lgkmcnt(4)
	v_mfma_f32_16x16x32_bf16 v[44:47], v[180:183], v[168:171], v[44:47]
	s_waitcnt lgkmcnt(1)
	v_mfma_f32_16x16x32_bf16 v[48:51], v[184:187], v[168:171], v[48:51]
	s_waitcnt lgkmcnt(0)
	v_mfma_f32_16x16x32_bf16 v[52:55], v[188:191], v[168:171], v[52:55]
; #define LAS __attribute__((address_space(3)))
; __device__ __forceinline__ unsigned cvt_pk_bf16(float lo, float hi) { unsigned r; asm volatile("v_cvt_pk_bf16_f32 %0, %1, %2" : "=v"(r) : "v"(lo), "v"(hi)); return r; }
; __device__ __forceinline__ void phase_C1(const Args& a, unsigned char* ws, const int bid, int l, LAS unsigned char* lds, int tid, int wave, int lane) {
;     ...
;             { const int q = qt * 16 + fr; const float csq = cs[q], eq = ecs[q];
;               f32x4 gd = accA[0];
; #pragma unroll
;               for (int kt = 1; kt < 8; ++kt) { const bool is = (kt == qt); gd.x = is ? accA[kt].x : gd.x; gd.y = is ? accA[kt].y : gd.y; gd.z = is ? accA[kt].z : gd.z; gd.w = is ? accA[kt].w : gd.w; }
; #pragma unroll
;               for (int kt = 0; kt < 8; ++kt) { const int k0 = kt * 16 + fq * 4;
;                   const bool kept = dir == 0 ? (kt < qt) : (kt > qt);
;                   const float f1 = __expf(csq - refarr[kt]); const f32x4 f2 = *(const LAS f32x4*)(f2dt + k0);
;                   float m[4];
; #pragma unroll
;                   for (int r = 0; r < 4; ++r) m[r] = kept ? accA[kt][r] * f1 * f2[r] : 0.f;
;                   u32x2 o; o.x = cvt_pk_bf16(m[0], m[1]); o.y = cvt_pk_bf16(m[2], m[3]);
;                   *(LAS u32x2*)(L_M + q * 272 + k0 * 2) = o; }
;               { const int k0 = qt * 16 + fq * 4; const f32x4 ck = *(const LAS f32x4*)(cs + k0), dk = *(const LAS f32x4*)(dtv + k0); float m[4];
.Lssd_m_section:
	ds_read_b32 v117, v127
	ds_read_b32 v116, v128
	v_cndmask_b32_e64 v169, v102, v98, s[10:11]
	v_cndmask_b32_e64 v170, v101, v97, s[10:11]
	v_cndmask_b32_e64 v171, v100, v96, s[10:11]
	v_cndmask_b32_e64 v168, v103, v99, s[10:11]
	s_waitcnt lgkmcnt(0)
	v_sub_f32_e32 v172, v117, v244
	v_mul_f32_e32 v172, 0x3fb8aa3b, v172
	v_exp_f32_e32 v176, v172
	s_nop 0
	v_readlane_b32 s0, v253, 52
	v_mul_f32_e32 v100, v100, v176
	v_mul_f32_e32 v101, v101, v176
	v_mul_f32_e32 v102, v102, v176
	v_mul_f32_e32 v100, v212, v100
	v_mul_f32_e32 v101, v213, v101
	v_mul_f32_e32 v102, v214, v102
	v_mul_f32_e32 v103, v103, v176
	v_cndmask_b32_e64 v100, 0, v100, s[44:45]
	v_cndmask_b32_e64 v101, 0, v101, s[44:45]
	v_cndmask_b32_e64 v102, 0, v102, s[44:45]
	v_mul_f32_e32 v103, v215, v103
	v_cndmask_b32_e64 v103, 0, v103, s[44:45]
	v_cvt_pk_bf16_f32 v100, v100, v101
	v_cvt_pk_bf16_f32 v101, v102, v103
	v_add_u32_e32 v102, v129, v108
	ds_write_b64 v102, v[100:101]
	v_readlane_b32 s0, v253, 53
	v_sub_f32_e32 v100, v117, v245
	v_mul_f32_e32 v100, 0x3fb8aa3b, v100
	v_exp_f32_e32 v172, v100
	s_nop 0
	v_mul_f32_e32 v96, v96, v172
	v_mul_f32_e32 v97, v97, v172
	v_mul_f32_e32 v96, v216, v96
	v_cndmask_b32_e64 v96, 0, v96, s[46:47]
	v_mul_f32_e32 v97, v217, v97
	v_mul_f32_e32 v98, v98, v172
	v_mul_f32_e32 v99, v99, v172
	v_cndmask_b32_e64 v97, 0, v97, s[46:47]
	v_mul_f32_e32 v98, v218, v98
	v_mul_f32_e32 v99, v219, v99
	v_cvt_pk_bf16_f32 v96, v96, v97
	v_cndmask_b32_e64 v98, 0, v98, s[46:47]
	v_cndmask_b32_e64 v99, 0, v99, s[46:47]
	v_cvt_pk_bf16_f32 v97, v98, v99
	ds_write_b64 v148, v[96:97]
	v_readlane_b32 s0, v253, 54
	v_mov_b32_e32 v172, 0
	v_sub_f32_e32 v96, v117, v246
	v_mul_f32_e32 v96, 0x3fb8aa3b, v96
	v_exp_f32_e32 v100, v96
	s_nop 0
	v_mul_f32_e32 v101, v88, v100
	v_mul_f32_e32 v96, v220, v101
	v_mul_f32_e32 v101, v89, v100
	v_cndmask_b32_e64 v96, 0, v96, s[48:49]
	v_mul_f32_e32 v97, v221, v101
	v_mul_f32_e32 v101, v90, v100
	v_mul_f32_e32 v100, v91, v100
	v_cndmask_b32_e64 v97, 0, v97, s[48:49]
	v_mul_f32_e32 v98, v222, v101
	v_mul_f32_e32 v99, v223, v100
	v_cvt_pk_bf16_f32 v96, v96, v97
	v_cndmask_b32_e64 v98, 0, v98, s[48:49]
	v_cndmask_b32_e64 v99, 0, v99, s[48:49]
	v_cvt_pk_bf16_f32 v97, v98, v99
	ds_write_b64 v149, v[96:97]
	v_readlane_b32 s0, v253, 55
	v_sub_f32_e32 v96, v117, v247
	v_mul_f32_e32 v96, 0x3fb8aa3b, v96
	v_exp_f32_e32 v100, v96
	s_nop 0
	v_mul_f32_e32 v101, v80, v100
	v_mul_f32_e32 v96, v224, v101
	v_mul_f32_e32 v101, v81, v100
	v_cndmask_b32_e64 v96, 0, v96, s[50:51]
	v_mul_f32_e32 v97, v225, v101
	v_mul_f32_e32 v101, v82, v100
	v_mul_f32_e32 v100, v83, v100
	v_cndmask_b32_e64 v97, 0, v97, s[50:51]
	v_mul_f32_e32 v98, v226, v101
	v_mul_f32_e32 v99, v227, v100
	v_cvt_pk_bf16_f32 v96, v96, v97
	v_cndmask_b32_e64 v98, 0, v98, s[50:51]
	v_cndmask_b32_e64 v99, 0, v99, s[50:51]
	v_cvt_pk_bf16_f32 v97, v98, v99
	ds_write_b64 v150, v[96:97]
	v_readlane_b32 s0, v253, 56
	v_sub_f32_e32 v96, v117, v248
	v_mul_f32_e32 v96, 0x3fb8aa3b, v96
	v_exp_f32_e32 v100, v96
	s_nop 0
	v_mul_f32_e32 v101, v92, v100
	v_mul_f32_e32 v96, v228, v101
	v_mul_f32_e32 v101, v93, v100
	v_cndmask_b32_e64 v96, 0, v96, s[52:53]
	v_mul_f32_e32 v97, v229, v101
	v_mul_f32_e32 v101, v94, v100
	v_mul_f32_e32 v100, v95, v100
	v_cndmask_b32_e64 v97, 0, v97, s[52:53]
	v_mul_f32_e32 v98, v230, v101
	v_mul_f32_e32 v99, v231, v100
	v_cvt_pk_bf16_f32 v96, v96, v97
	v_cndmask_b32_e64 v98, 0, v98, s[52:53]
	v_cndmask_b32_e64 v99, 0, v99, s[52:53]
	v_cvt_pk_bf16_f32 v97, v98, v99
	ds_write_b64 v151, v[96:97]
	v_readlane_b32 s0, v253, 57
	v_sub_f32_e32 v96, v117, v249
	v_mul_f32_e32 v96, 0x3fb8aa3b, v96
	v_exp_f32_e32 v100, v96
	s_nop 0
	v_mul_f32_e32 v101, v84, v100
	v_mul_f32_e32 v96, v232, v101
	v_mul_f32_e32 v101, v85, v100
	v_cndmask_b32_e64 v96, 0, v96, s[54:55]
	v_mul_f32_e32 v97, v233, v101
	v_mul_f32_e32 v101, v86, v100
	v_mul_f32_e32 v100, v87, v100
	v_cndmask_b32_e64 v97, 0, v97, s[54:55]
	v_mul_f32_e32 v98, v234, v101
	v_mul_f32_e32 v99, v235, v100
	v_cvt_pk_bf16_f32 v96, v96, v97
	v_cndmask_b32_e64 v98, 0, v98, s[54:55]
	v_cndmask_b32_e64 v99, 0, v99, s[54:55]
	v_cvt_pk_bf16_f32 v97, v98, v99
	ds_write_b64 v152, v[96:97]
	v_readlane_b32 s0, v253, 58
	v_sub_f32_e32 v96, v117, v250
	v_mul_f32_e32 v96, 0x3fb8aa3b, v96
	v_exp_f32_e32 v100, v96
	s_nop 0
	v_mul_f32_e32 v101, v76, v100
	v_mul_f32_e32 v96, v236, v101
	v_mul_f32_e32 v101, v77, v100
	v_cndmask_b32_e64 v96, 0, v96, s[56:57]
	v_mul_f32_e32 v97, v237, v101
	v_mul_f32_e32 v101, v78, v100
	v_mul_f32_e32 v100, v79, v100
	v_cndmask_b32_e64 v97, 0, v97, s[56:57]
	v_mul_f32_e32 v98, v238, v101
	v_mul_f32_e32 v99, v239, v100
	v_cvt_pk_bf16_f32 v96, v96, v97
	v_cndmask_b32_e64 v98, 0, v98, s[56:57]
	v_cndmask_b32_e64 v99, 0, v99, s[56:57]
	v_cvt_pk_bf16_f32 v97, v98, v99
	ds_write_b64 v153, v[96:97]
	v_sub_f32_e32 v96, v117, v251
	v_mul_f32_e32 v96, 0x3fb8aa3b, v96
	v_exp_f32_e32 v100, v96
	s_nop 0
	v_mul_f32_e32 v101, v72, v100
	v_mul_f32_e32 v96, v240, v101
	v_mul_f32_e32 v101, v73, v100
	v_mul_f32_e32 v97, v241, v101
	v_mul_f32_e32 v101, v74, v100
	v_mul_f32_e32 v100, v75, v100
	v_cndmask_b32_e64 v96, 0, v96, s[58:59]
	v_cndmask_b32_e64 v97, 0, v97, s[58:59]
	v_mul_f32_e32 v98, v242, v101
	v_mul_f32_e32 v99, v243, v100
	v_cndmask_b32_e64 v98, 0, v98, s[58:59]
	v_cndmask_b32_e64 v99, 0, v99, s[58:59]
	v_cvt_pk_bf16_f32 v96, v96, v97
	v_cvt_pk_bf16_f32 v97, v98, v99
	ds_write_b64 v154, v[96:97]
	ds_read_b128 v[100:103], v130
	ds_read_b128 v[96:99], v131
	s_and_saveexec_b64 s[0:1], s[60:61]
	s_cbranch_execz .LBB0_123
	v_cndmask_b32_e64 v88, v171, v88, s[12:13]
	v_cndmask_b32_e64 v80, v88, v80, s[14:15]
	s_waitcnt lgkmcnt(1)
	v_sub_f32_e32 v88, v117, v100
	v_mul_f32_e32 v88, 0x3fb8aa3b, v88
	v_cndmask_b32_e64 v80, v80, v92, s[16:17]
	v_exp_f32_e32 v88, v88
	v_cndmask_b32_e64 v80, v80, v84, s[18:19]
	v_cndmask_b32_e64 v76, v80, v76, s[20:21]
	v_cndmask_b32_e64 v72, v76, v72, s[22:23]
	v_mul_f32_e32 v72, v72, v88
	s_waitcnt lgkmcnt(0)
	v_mul_f32_e32 v172, v96, v72

; #define LAS __attribute__((address_space(3)))
; __device__ __forceinline__ unsigned cvt_pk_bf16(float lo, float hi) { unsigned r; asm volatile("v_cvt_pk_bf16_f32 %0, %1, %2" : "=v"(r) : "v"(lo), "v"(hi)); return r; }
; #define MFMA16(a, b, c) __builtin_amdgcn_mfma_f32_16x16x32_bf16((a), (b), (c), 0, 0, 0)
; #define TRB(base, krow0, col0, t) __builtin_amdgcn_ds_read_tr16_b64_v4i16((LAS s16x4*)((base) + trB + ((krow0) + 4 * (t)) * 272 + (col0) * 2))
; #define TRX(base, krow0, col0, t) __builtin_amdgcn_ds_read_tr16_b64_v4i16((LAS s16x4*)((base) + trX + ((krow0) + 4 * (t)) * 144 + (col0) * 2))
; __device__ __forceinline__ void phase_C1(const Args& a, unsigned char* ws, const int bid, int l, LAS unsigned char* lds, int tid, int wave, int lane) {
;     ...
;             { const float etot = __expf(totp[0]);
; #pragma unroll
;               for (int j = 0; j < 4; ++j) Hacc[j] = Hacc[j] * etot;
; #pragma unroll
;               for (int s = 0; s < 4; ++s) { const s16x4 xlo = TRX(L_X, 32 * s, 16 * wr, 0), xhi = TRX(L_X, 32 * s, 16 * wr, 1);
;                   const f32x4 w0 = *(const LAS f32x4*)(wgt + s * 32 + fq * 8), w1 = *(const LAS f32x4*)(wgt + s * 32 + fq * 8 + 4);
;                   s16x4 blo[4], bhi[4];
; #pragma unroll
;                   for (int j = 0; j < 4; ++j) { blo[j] = TRB(L_B, 32 * s, 16 * (4 * wc + j), 0); bhi[j] = TRB(L_B, 32 * s, 16 * (4 * wc + j), 1); }
;                   __builtin_amdgcn_sched_barrier(0);
;                   const u32x2 xl = __builtin_bit_cast(u32x2, xlo), xh = __builtin_bit_cast(u32x2, xhi);
;                   u32x4 xs; xs.x = cvt_pk_bf16(bflo(xl.x) * w0.x, bfhi(xl.x) * w0.y); xs.y = cvt_pk_bf16(bflo(xl.y) * w0.z, bfhi(xl.y) * w0.w);
;                   xs.z = cvt_pk_bf16(bflo(xh.x) * w1.x, bfhi(xh.x) * w1.y); xs.w = cvt_pk_bf16(bflo(xh.y) * w1.z, bfhi(xh.y) * w1.w);
;                   const bf16x8 xq = __builtin_bit_cast(bf16x8, xs);
; #pragma unroll
;                   for (int j = 0; j < 4; ++j) { const bf16x8 bt = (bf16x8){blo[j].x, blo[j].y, blo[j].z, blo[j].w, bhi[j].x, bhi[j].y, bhi[j].z, bhi[j].w};
;                       Hacc[j] = MFMA16(bt, xq, Hacc[j]); }
;                   __builtin_amdgcn_sched_barrier(0); } }
.Lssd_alt_order:
	v_mov_b32_e32 v116, s87
	ds_read_b32 v116, v116
	s_waitcnt lgkmcnt(0)
	v_mul_f32_e32 v116, 0x3fb8aa3b, v116
	v_exp_f32_e32 v116, v116
	s_nop 0
	v_pk_mul_f32 v[42:43], v[42:43], v[116:117] op_sel_hi:[1,0]
	v_pk_mul_f32 v[40:41], v[40:41], v[116:117] op_sel_hi:[1,0]
	v_pk_mul_f32 v[46:47], v[46:47], v[116:117] op_sel_hi:[1,0]
	v_pk_mul_f32 v[44:45], v[44:45], v[116:117] op_sel_hi:[1,0]
	v_pk_mul_f32 v[50:51], v[50:51], v[116:117] op_sel_hi:[1,0]
	v_pk_mul_f32 v[48:49], v[48:49], v[116:117] op_sel_hi:[1,0]
	v_pk_mul_f32 v[54:55], v[54:55], v[116:117] op_sel_hi:[1,0]
	v_pk_mul_f32 v[52:53], v[52:53], v[116:117] op_sel_hi:[1,0]
	ds_read_b64_tr_b16 v[116:117], v140
	ds_read_b64_tr_b16 v[192:193], v140 offset:576
	ds_read_b128 v[168:171], v125
	ds_read_b128 v[172:175], v125 offset:16
	ds_read_b64_tr_b16 v[178:179], v141 offset:35904
	ds_read_b64_tr_b16 v[176:177], v141 offset:34816
	ds_read_b64_tr_b16 v[180:181], v141 offset:34848
	ds_read_b64_tr_b16 v[182:183], v141 offset:35936
	ds_read_b64_tr_b16 v[184:185], v141 offset:34880
	ds_read_b64_tr_b16 v[186:187], v141 offset:35968
	ds_read_b64_tr_b16 v[188:189], v141 offset:34912
	ds_read_b64_tr_b16 v[190:191], v141 offset:36000
	s_waitcnt lgkmcnt(11)
	v_lshlrev_b32_e32 v194, 16, v116
	v_and_b32_e32 v116, 0xffff0000, v116
	s_waitcnt lgkmcnt(9)
	v_mul_f32_e32 v168, v168, v194
	v_mul_f32_e32 v116, v169, v116
	v_cvt_pk_bf16_f32 v168, v168, v116
	v_lshlrev_b32_e32 v116, 16, v117
	v_and_b32_e32 v117, 0xffff0000, v117
	v_mul_f32_e32 v116, v170, v116
	v_mul_f32_e32 v117, v171, v117
	v_cvt_pk_bf16_f32 v169, v116, v117
	v_lshlrev_b32_e32 v116, 16, v192
	v_and_b32_e32 v117, 0xffff0000, v192
	s_waitcnt lgkmcnt(8)
	v_mul_f32_e32 v116, v172, v116
	v_mul_f32_e32 v117, v173, v117
	v_cvt_pk_bf16_f32 v170, v116, v117
	v_lshlrev_b32_e32 v116, 16, v193
	v_and_b32_e32 v117, 0xffff0000, v193
	v_mul_f32_e32 v116, v174, v116
	v_mul_f32_e32 v117, v175, v117
	v_cvt_pk_bf16_f32 v171, v116, v117
	s_waitcnt lgkmcnt(6)
	v_mfma_f32_16x16x32_bf16 v[40:43], v[176:179], v[168:171], v[40:43]
	s_waitcnt lgkmcnt(4)
	v_mfma_f32_16x16x32_bf16 v[44:47], v[180:183], v[168:171], v[44:47]
	s_waitcnt lgkmcnt(2)
	v_mfma_f32_16x16x32_bf16 v[48:51], v[184:187], v[168:171], v[48:51]
	s_waitcnt lgkmcnt(0)
	v_mfma_f32_16x16x32_bf16 v[52:55], v[188:191], v[168:171], v[52:55]
	ds_read_b128 v[168:171], v125 offset:128
	ds_read_b128 v[172:175], v125 offset:144
	ds_read_b64_tr_b16 v[116:117], v140 offset:4608
	ds_read_b64_tr_b16 v[192:193], v140 offset:5184
	ds_read_b64_tr_b16 v[176:177], v141 offset:43520
	ds_read_b64_tr_b16 v[180:181], v141 offset:43552
	ds_read_b64_tr_b16 v[178:179], v141 offset:44608
	ds_read_b64_tr_b16 v[182:183], v141 offset:44640
	ds_read_b64_tr_b16 v[184:185], v141 offset:43584
	ds_read_b64_tr_b16 v[188:189], v141 offset:43616
	ds_read_b64_tr_b16 v[186:187], v141 offset:44672
	ds_read_b64_tr_b16 v[190:191], v141 offset:44704
	s_waitcnt lgkmcnt(9)
	v_lshlrev_b32_e32 v194, 16, v116
	v_and_b32_e32 v116, 0xffff0000, v116
	v_mul_f32_e32 v168, v168, v194
	v_mul_f32_e32 v116, v169, v116
	v_cvt_pk_bf16_f32 v168, v168, v116
	v_lshlrev_b32_e32 v116, 16, v117
	v_and_b32_e32 v117, 0xffff0000, v117
	v_mul_f32_e32 v116, v170, v116
	v_mul_f32_e32 v117, v171, v117
	v_cvt_pk_bf16_f32 v169, v116, v117
	s_waitcnt lgkmcnt(8)
	v_lshlrev_b32_e32 v116, 16, v192
	v_and_b32_e32 v117, 0xffff0000, v192
	v_mul_f32_e32 v116, v172, v116
	v_mul_f32_e32 v117, v173, v117
	v_cvt_pk_bf16_f32 v170, v116, v117
	v_lshlrev_b32_e32 v116, 16, v193
	v_and_b32_e32 v117, 0xffff0000, v193
	v_mul_f32_e32 v116, v174, v116
	v_mul_f32_e32 v117, v175, v117
	v_cvt_pk_bf16_f32 v171, v116, v117
	s_waitcnt lgkmcnt(5)
	v_mfma_f32_16x16x32_bf16 v[40:43], v[176:179], v[168:171], v[40:43]
	s_waitcnt lgkmcnt(4)
	v_mfma_f32_16x16x32_bf16 v[44:47], v[180:183], v[168:171], v[44:47]
	s_waitcnt lgkmcnt(1)
	v_mfma_f32_16x16x32_bf16 v[48:51], v[184:187], v[168:171], v[48:51]
	s_waitcnt lgkmcnt(0)
	v_mfma_f32_16x16x32_bf16 v[52:55], v[188:191], v[168:171], v[52:55]
	ds_read_b128 v[168:171], v125 offset:256
	ds_read_b128 v[172:175], v125 offset:272
	ds_read_b64_tr_b16 v[116:117], v140 offset:9216
	ds_read_b64_tr_b16 v[192:193], v140 offset:9792
	ds_read_b64_tr_b16 v[176:177], v141 offset:52224
	ds_read_b64_tr_b16 v[180:181], v141 offset:52256
	ds_read_b64_tr_b16 v[178:179], v141 offset:53312
	ds_read_b64_tr_b16 v[182:183], v141 offset:53344
	ds_read_b64_tr_b16 v[184:185], v141 offset:52288
	ds_read_b64_tr_b16 v[188:189], v141 offset:52320
	ds_read_b64_tr_b16 v[186:187], v141 offset:53376
	ds_read_b64_tr_b16 v[190:191], v141 offset:53408
	s_waitcnt lgkmcnt(9)
	v_lshlrev_b32_e32 v194, 16, v116
	v_and_b32_e32 v116, 0xffff0000, v116
	v_mul_f32_e32 v168, v168, v194
	v_mul_f32_e32 v116, v169, v116
	v_cvt_pk_bf16_f32 v168, v168, v116
	v_lshlrev_b32_e32 v116, 16, v117
	v_and_b32_e32 v117, 0xffff0000, v117
	v_mul_f32_e32 v116, v170, v116
	v_mul_f32_e32 v117, v171, v117
	v_cvt_pk_bf16_f32 v169, v116, v117
	s_waitcnt lgkmcnt(8)
	v_lshlrev_b32_e32 v116, 16, v192
	v_and_b32_e32 v117, 0xffff0000, v192
	v_mul_f32_e32 v116, v172, v116
	v_mul_f32_e32 v117, v173, v117
	v_cvt_pk_bf16_f32 v170, v116, v117
	v_lshlrev_b32_e32 v116, 16, v193
	v_and_b32_e32 v117, 0xffff0000, v193
	v_mul_f32_e32 v116, v174, v116
	v_mul_f32_e32 v117, v175, v117
	v_cvt_pk_bf16_f32 v171, v116, v117
	s_waitcnt lgkmcnt(5)
	v_mfma_f32_16x16x32_bf16 v[40:43], v[176:179], v[168:171], v[40:43]
	s_waitcnt lgkmcnt(4)
	v_mfma_f32_16x16x32_bf16 v[44:47], v[180:183], v[168:171], v[44:47]
	s_waitcnt lgkmcnt(1)
	v_mfma_f32_16x16x32_bf16 v[48:51], v[184:187], v[168:171], v[48:51]
	s_waitcnt lgkmcnt(0)
; #define LAS __attribute__((address_space(3)))
; __device__ __forceinline__ unsigned cvt_pk_bf16(float lo, float hi) { unsigned r; asm volatile("v_cvt_pk_bf16_f32 %0, %1, %2" : "=v"(r) : "v"(lo), "v"(hi)); return r; }
; __device__ __forceinline__ void phase_C1(const Args& a, unsigned char* ws, const int bid, int l, LAS unsigned char* lds, int tid, int wave, int lane) {
;     ...
;             {
;                 bf16x8 cqv[2], bq[2][4], hq[2][2];
;     ...
;                 SSD_LDH(0, 0);
; #pragma unroll
;                 for (int h2 = 0; h2 < 8; ++h2) { const int cb = h2 & 1, s_ = h2 >> 1, hf_ = h2 & 1;
;                     if (h2 < 7) SSD_LDH(cb ^ 1, h2 + 1);
;                     __builtin_amdgcn_sched_barrier(0);
; #pragma unroll
;                     for (int k = 0; k < 4; ++k) accA[4 * hf_ + k] = MFMA16(bq[cb][k], cqv[s_ & 1], accA[4 * hf_ + k]);
; #pragma unroll
;                     for (int p = 0; p < 2; ++p) accC[2 * hf_ + p] = MFMA16(hq[cb][p], cqv[s_ & 1], accC[2 * hf_ + p]);
;                     __builtin_amdgcn_sched_barrier(0); }
;     ...
;               for (int s = 0; s < 4; ++s) { const s16x4 xlo = TRX(L_X, 32 * s, 16 * wr, 0), xhi = TRX(L_X, 32 * s, 16 * wr, 1);
;                   const f32x4 w0 = *(const LAS f32x4*)(wgt + s * 32 + fq * 8), w1 = *(const LAS f32x4*)(wgt + s * 32 + fq * 8 + 4);
;                   s16x4 blo[4], bhi[4];
; #pragma unroll
;                   for (int j = 0; j < 4; ++j) { blo[j] = TRB(L_B, 32 * s, 16 * (4 * wc + j), 0); bhi[j] = TRB(L_B, 32 * s, 16 * (4 * wc + j), 1); }
;                   __builtin_amdgcn_sched_barrier(0);
;                   const u32x2 xl = __builtin_bit_cast(u32x2, xlo), xh = __builtin_bit_cast(u32x2, xhi);
;                   u32x4 xs; xs.x = cvt_pk_bf16(bflo(xl.x) * w0.x, bfhi(xl.x) * w0.y); xs.y = cvt_pk_bf16(bflo(xl.y) * w0.z, bfhi(xl.y) * w0.w);
;                   xs.z = cvt_pk_bf16(bflo(xh.x) * w1.x, bfhi(xh.x) * w1.y); xs.w = cvt_pk_bf16(bflo(xh.y) * w1.z, bfhi(xh.y) * w1.w);
;                   const bf16x8 xq = __builtin_bit_cast(bf16x8, xs);
; #pragma unroll
;                   for (int j = 0; j < 4; ++j) { const bf16x8 bt = (bf16x8){blo[j].x, blo[j].y, blo[j].z, blo[j].w, bhi[j].x, bhi[j].y, bhi[j].z, bhi[j].w};
;                       Hacc[j] = MFMA16(bt, xq, Hacc[j]); }
;                   __builtin_amdgcn_sched_barrier(0); } }
	v_mfma_f32_16x16x32_bf16 v[52:55], v[188:191], v[168:171], v[52:55]
	ds_read_b128 v[168:171], v125 offset:384
	ds_read_b128 v[172:175], v125 offset:400
	ds_read_b64_tr_b16 v[116:117], v140 offset:13824
	ds_read_b64_tr_b16 v[192:193], v140 offset:14400
	ds_read_b64_tr_b16 v[176:177], v141 offset:60928
	ds_read_b64_tr_b16 v[180:181], v141 offset:60960
	ds_read_b64_tr_b16 v[178:179], v141 offset:62016
	ds_read_b64_tr_b16 v[182:183], v141 offset:62048
	ds_read_b64_tr_b16 v[184:185], v141 offset:60992
	ds_read_b64_tr_b16 v[188:189], v141 offset:61024
	ds_read_b64_tr_b16 v[186:187], v141 offset:62080
	ds_read_b64_tr_b16 v[190:191], v141 offset:62112
	s_waitcnt lgkmcnt(9)
	v_lshlrev_b32_e32 v194, 16, v116
	v_and_b32_e32 v116, 0xffff0000, v116
	v_mul_f32_e32 v168, v168, v194
	v_mul_f32_e32 v116, v169, v116
	v_cvt_pk_bf16_f32 v168, v168, v116
	v_lshlrev_b32_e32 v116, 16, v117
	v_and_b32_e32 v117, 0xffff0000, v117
	v_mul_f32_e32 v116, v170, v116
	v_mul_f32_e32 v117, v171, v117
	v_cvt_pk_bf16_f32 v169, v116, v117
	s_waitcnt lgkmcnt(8)
	v_lshlrev_b32_e32 v116, 16, v192
	v_and_b32_e32 v117, 0xffff0000, v192
	v_mul_f32_e32 v116, v172, v116
	v_mul_f32_e32 v117, v173, v117
	v_cvt_pk_bf16_f32 v170, v116, v117
	v_lshlrev_b32_e32 v116, 16, v193
	v_and_b32_e32 v117, 0xffff0000, v193
	v_mul_f32_e32 v116, v174, v116
	v_mul_f32_e32 v117, v175, v117
	v_cvt_pk_bf16_f32 v171, v116, v117
	s_waitcnt lgkmcnt(5)
	v_mfma_f32_16x16x32_bf16 v[40:43], v[176:179], v[168:171], v[40:43]
	s_waitcnt lgkmcnt(4)
	v_mfma_f32_16x16x32_bf16 v[44:47], v[180:183], v[168:171], v[44:47]
	s_waitcnt lgkmcnt(1)
	v_mfma_f32_16x16x32_bf16 v[48:51], v[184:187], v[168:171], v[48:51]
	s_waitcnt lgkmcnt(0)
	v_mfma_f32_16x16x32_bf16 v[52:55], v[188:191], v[168:171], v[52:55]
	v_add_u32_e32 v116, s33, v118
	ds_read_b128 v[56:59], v118 offset:34816
	ds_read_b128 v[60:63], v118 offset:39168
	ds_read_b128 v[64:67], v118 offset:43520
	ds_read_b128 v[68:71], v118 offset:47872
	ds_read_b128 v[72:75], v116
	ds_read_b128 v[76:79], v147
	ds_read_b128 v[80:83], v118 offset:52224
	ds_read_b128 v[84:87], v118 offset:56576
	ds_read_b128 v[88:91], v118 offset:60928
	ds_read_b128 v[92:95], v118 offset:65280
	ds_read_b128 v[96:99], v147 offset:1088
	ds_read_b128 v[100:103], v147 offset:8704
	ds_read_b128 v[168:171], v147 offset:9792
	s_waitcnt lgkmcnt(8)
	v_mfma_f32_16x16x32_bf16 v[56:59], v[56:59], v[72:75], 0
	v_mfma_f32_16x16x32_bf16 v[60:63], v[60:63], v[72:75], 0
	v_mfma_f32_16x16x32_bf16 v[64:67], v[64:67], v[72:75], 0
	v_mfma_f32_16x16x32_bf16 v[68:71], v[68:71], v[72:75], 0
	s_waitcnt lgkmcnt(7)
	v_mfma_f32_16x16x32_bf16 v[76:79], v[76:79], v[72:75], 0
	s_waitcnt lgkmcnt(2)
	v_mfma_f32_16x16x32_bf16 v[96:99], v[96:99], v[72:75], 0
	ds_read_b128 v[172:175], v118 offset:34880
	ds_read_b128 v[176:179], v118 offset:39232
	ds_read_b128 v[180:183], v118 offset:43584
	ds_read_b128 v[184:187], v118 offset:47936
	ds_read_b128 v[188:191], v116 offset:64
	ds_read_b128 v[212:215], v147 offset:64
	ds_read_b128 v[216:219], v147 offset:1152
	v_mfma_f32_16x16x32_bf16 v[80:83], v[80:83], v[72:75], 0
	v_mfma_f32_16x16x32_bf16 v[84:87], v[84:87], v[72:75], 0
	v_mfma_f32_16x16x32_bf16 v[88:91], v[88:91], v[72:75], 0
	v_mfma_f32_16x16x32_bf16 v[92:95], v[92:95], v[72:75], 0
	s_waitcnt lgkmcnt(8)
	v_mfma_f32_16x16x32_bf16 v[100:103], v[100:103], v[72:75], 0
	s_waitcnt lgkmcnt(7)
	v_mfma_f32_16x16x32_bf16 v[72:75], v[168:171], v[72:75], 0
	ds_read_b128 v[168:171], v118 offset:52288
	ds_read_b128 v[220:223], v118 offset:56640
	ds_read_b128 v[224:227], v118 offset:60992
	ds_read_b128 v[228:231], v118 offset:65344
	ds_read_b128 v[232:235], v147 offset:8768
	ds_read_b128 v[236:239], v147 offset:9856
	s_waitcnt lgkmcnt(8)
	v_mfma_f32_16x16x32_bf16 v[56:59], v[172:175], v[188:191], v[56:59]
	v_mfma_f32_16x16x32_bf16 v[60:63], v[176:179], v[188:191], v[60:63]
	v_mfma_f32_16x16x32_bf16 v[64:67], v[180:183], v[188:191], v[64:67]
	v_mfma_f32_16x16x32_bf16 v[68:71], v[184:187], v[188:191], v[68:71]
	s_waitcnt lgkmcnt(7)
	v_mfma_f32_16x16x32_bf16 v[76:79], v[212:215], v[188:191], v[76:79]
	s_waitcnt lgkmcnt(6)
; #define MFMA16(a, b, c) __builtin_amdgcn_mfma_f32_16x16x32_bf16((a), (b), (c), 0, 0, 0)
; __device__ __forceinline__ void phase_C1(const Args& a, unsigned char* ws, const int bid, int l, LAS unsigned char* lds, int tid, int wave, int lane) {
;     ...
;             {
;                 bf16x8 cqv[2], bq[2][4], hq[2][2];
;     ...
;                 SSD_LDH(0, 0);
; #pragma unroll
;                 for (int h2 = 0; h2 < 8; ++h2) { const int cb = h2 & 1, s_ = h2 >> 1, hf_ = h2 & 1;
;                     if (h2 < 7) SSD_LDH(cb ^ 1, h2 + 1);
;                     __builtin_amdgcn_sched_barrier(0);
; #pragma unroll
;                     for (int k = 0; k < 4; ++k) accA[4 * hf_ + k] = MFMA16(bq[cb][k], cqv[s_ & 1], accA[4 * hf_ + k]);
; #pragma unroll
;                     for (int p = 0; p < 2; ++p) accC[2 * hf_ + p] = MFMA16(hq[cb][p], cqv[s_ & 1], accC[2 * hf_ + p]);
;                     __builtin_amdgcn_sched_barrier(0); }
	v_mfma_f32_16x16x32_bf16 v[96:99], v[216:219], v[188:191], v[96:99]
	ds_read_b128 v[172:175], v118 offset:34944
	ds_read_b128 v[176:179], v118 offset:39296
	ds_read_b128 v[180:183], v118 offset:43648
	ds_read_b128 v[184:187], v118 offset:48000
	ds_read_b128 v[212:215], v116 offset:128
	ds_read_b128 v[216:219], v147 offset:128
	ds_read_b128 v[240:243], v147 offset:1216
	s_waitcnt lgkmcnt(12)
	v_mfma_f32_16x16x32_bf16 v[80:83], v[168:171], v[188:191], v[80:83]
	s_waitcnt lgkmcnt(11)
	v_mfma_f32_16x16x32_bf16 v[84:87], v[220:223], v[188:191], v[84:87]
	s_waitcnt lgkmcnt(10)
	v_mfma_f32_16x16x32_bf16 v[88:91], v[224:227], v[188:191], v[88:91]
	s_waitcnt lgkmcnt(9)
	v_mfma_f32_16x16x32_bf16 v[92:95], v[228:231], v[188:191], v[92:95]
	s_waitcnt lgkmcnt(8)
	v_mfma_f32_16x16x32_bf16 v[100:103], v[232:235], v[188:191], v[100:103]
	s_waitcnt lgkmcnt(7)
	v_mfma_f32_16x16x32_bf16 v[72:75], v[236:239], v[188:191], v[72:75]
	ds_read_b128 v[168:171], v118 offset:52352
	ds_read_b128 v[188:191], v118 offset:56704
	ds_read_b128 v[220:223], v118 offset:61056
	ds_read_b128 v[224:227], v118 offset:65408
	ds_read_b128 v[228:231], v147 offset:8832
	ds_read_b128 v[232:235], v147 offset:9920
	s_waitcnt lgkmcnt(8)
	v_mfma_f32_16x16x32_bf16 v[56:59], v[172:175], v[212:215], v[56:59]
	v_mfma_f32_16x16x32_bf16 v[60:63], v[176:179], v[212:215], v[60:63]
	v_mfma_f32_16x16x32_bf16 v[64:67], v[180:183], v[212:215], v[64:67]
	v_mfma_f32_16x16x32_bf16 v[68:71], v[184:187], v[212:215], v[68:71]
	s_waitcnt lgkmcnt(7)
	v_mfma_f32_16x16x32_bf16 v[76:79], v[216:219], v[212:215], v[76:79]
	s_waitcnt lgkmcnt(6)
	v_mfma_f32_16x16x32_bf16 v[172:175], v[240:243], v[212:215], v[96:99]
	s_nop 2
	ds_read_b128 v[96:99], v118 offset:35008
	ds_read_b128 v[176:179], v118 offset:39360
	ds_read_b128 v[180:183], v118 offset:43712
	ds_read_b128 v[184:187], v118 offset:48064
	ds_read_b128 v[216:219], v116 offset:192
	ds_read_b128 v[236:239], v147 offset:192
	ds_read_b128 v[240:243], v147 offset:1280
	s_waitcnt lgkmcnt(12)
	v_mfma_f32_16x16x32_bf16 v[168:171], v[168:171], v[212:215], v[80:83]
	s_waitcnt lgkmcnt(11)
	v_mfma_f32_16x16x32_bf16 v[84:87], v[188:191], v[212:215], v[84:87]
	s_waitcnt lgkmcnt(10)
	v_mfma_f32_16x16x32_bf16 v[188:191], v[220:223], v[212:215], v[88:91]
	s_waitcnt lgkmcnt(9)
	v_mfma_f32_16x16x32_bf16 v[220:223], v[224:227], v[212:215], v[92:95]
	s_waitcnt lgkmcnt(8)
	v_mfma_f32_16x16x32_bf16 v[224:227], v[228:231], v[212:215], v[100:103]
	s_waitcnt lgkmcnt(7)
	v_mfma_f32_16x16x32_bf16 v[212:215], v[232:235], v[212:215], v[72:75]
	s_nop 2
	ds_read_b128 v[72:75], v118 offset:52416
	ds_read_b128 v[228:231], v118 offset:56768
	ds_read_b128 v[232:235], v118 offset:61120
	ds_read_b128 v[244:247], v118 offset:65472
	ds_read_b128 v[248:251], v147 offset:8896
	ds_read_b128 v[192:195], v147 offset:9984
	s_waitcnt lgkmcnt(8)
	v_mfma_f32_16x16x32_bf16 v[100:103], v[96:99], v[216:219], v[56:59]
	v_mfma_f32_16x16x32_bf16 v[96:99], v[176:179], v[216:219], v[60:63]
	v_mfma_f32_16x16x32_bf16 v[88:91], v[180:183], v[216:219], v[64:67]
	v_mfma_f32_16x16x32_bf16 v[80:83], v[184:187], v[216:219], v[68:71]
	s_waitcnt lgkmcnt(7)
	v_mfma_f32_16x16x32_bf16 v[68:71], v[236:239], v[216:219], v[76:79]
	s_waitcnt lgkmcnt(6)
	v_mfma_f32_16x16x32_bf16 v[64:67], v[240:243], v[216:219], v[172:175]
	s_waitcnt lgkmcnt(5)
	v_mfma_f32_16x16x32_bf16 v[92:95], v[72:75], v[216:219], v[168:171]
	s_waitcnt lgkmcnt(4)
	v_mfma_f32_16x16x32_bf16 v[84:87], v[228:231], v[216:219], v[84:87]
	s_waitcnt lgkmcnt(3)
	v_mfma_f32_16x16x32_bf16 v[76:79], v[232:235], v[216:219], v[188:191]
	s_waitcnt lgkmcnt(2)
	v_mfma_f32_16x16x32_bf16 v[72:75], v[244:247], v[216:219], v[220:223]
	s_waitcnt lgkmcnt(1)
	v_mfma_f32_16x16x32_bf16 v[60:63], v[248:251], v[216:219], v[224:227]
	s_waitcnt lgkmcnt(0)
	v_mfma_f32_16x16x32_bf16 v[56:59], v[192:195], v[216:219], v[212:215]
	v_mov_b32_e32 v116, 0x22e00
	ds_read_b128 v[244:247], v116
	ds_read_b128 v[248:251], v116 offset:16
	ds_read_b128 v[216:219], v133
	ds_read_b128 v[220:223], v134
	ds_read_b128 v[224:227], v135
	ds_read_b128 v[228:231], v136
	ds_read_b128 v[232:235], v137
	ds_read_b128 v[236:239], v138
	ds_read_b128 v[240:243], v139
	ds_read_b128 v[212:215], v132
	s_branch .Lssd_m_section

; #define INP(k) inp_(a.in[k])
; __device__ __forceinline__ void phase_C0(const Args& a, unsigned char* ws, const int bid, int l, LAS unsigned char* lds, int tid, int wave, int lane) {
;     ...
;     { const bf16_t* z = (const bf16_t*)(ws + WS_Z); float* DT = (float*)(ws + WS_DT); const float* dtb = INP(11) + l * 64;
;       for (int idx = bid * 512 + tid; idx < T * 64; idx += G * 512) { const int t = idx >> 6, j = idx & 63;
;           const float xr = bf1(z[(size_t)t * ZW + ZC_DT + j]) + dtb[j];
;           const float e = __expf(-fabsf(xr)), u = 1.f + e;
;           const float l1p = (u == 1.f) ? e : __logf(u) * e * __builtin_amdgcn_rcpf(u - 1.f);
;           DT[idx] = fmaxf(xr, 0.f) + l1p; } }
.LBB0_129:
	s_cmp_gt_i32 s60, 1
	s_mov_b64 s[4:5], -1
	s_cbranch_scc0 .LBB0_186
	s_waitcnt vmcnt(11)
	v_lshl_add_u32 v0, s68, 9, v164
	s_mov_b32 s3, 0x210000
	s_mov_b64 s[6:7], 0
	v_cmp_gt_i32_e32 vcc, s3, v0
	s_and_saveexec_b64 s[4:5], vcc
	s_cbranch_execz .LBB0_133
	v_readlane_b32 s8, v254, 13
	s_lshl_b64 s[6:7], s[6:7], 2
	v_readlane_b32 s14, v254, 19
	v_readlane_b32 s15, v254, 20
	s_add_u32 s3, s14, s6
	s_addc_u32 s8, s15, s7
	s_lshl_b32 s6, s82, 6
	s_ashr_i32 s7, s6, 31
	s_lshl_b64 s[6:7], s[6:7], 2
	v_readlane_b32 s9, v254, 14
	s_add_u32 s6, s3, s6
	s_addc_u32 s7, s8, s7
	v_readlane_b32 s8, v254, 47
	v_lshlrev_b32_e32 v160, 1, v206
	v_readlane_b32 s9, v254, 48
	v_readlane_b32 s3, v253, 29
	v_readlane_b32 s12, v254, 17
	v_lshl_add_u64 v[2:3], s[8:9], 0, v[160:161]
	v_lshlrev_b32_e32 v160, 2, v206
	v_readlane_b32 s13, v254, 18
	s_waitcnt vmcnt(10)
	v_lshl_add_u64 v[4:5], s[6:7], 0, v[160:161]
	s_add_u32 s6, s3, s40
	v_readlane_b32 s3, v253, 30
	v_readlane_b32 s10, v254, 15
	v_readlane_b32 s11, v254, 16
	v_readlane_b32 s12, v253, 31
	s_mov_b64 s[8:9], 0x19b04000
	v_ashrrev_i32_e32 v1, 31, v0
	s_addc_u32 s7, s3, s41
	v_readlane_b32 s13, v253, 32
	v_readlane_b32 s10, v254, 37
	v_lshl_add_u64 v[2:3], v[2:3], 0, s[8:9]
	v_lshl_add_u64 v[6:7], v[0:1], 2, s[6:7]
	s_mov_b64 s[6:7], 0
	v_readlane_b32 s16, v254, 21
	v_readlane_b32 s17, v254, 22
	v_readlane_b32 s18, v254, 23
	v_readlane_b32 s19, v254, 24
	v_readlane_b32 s20, v254, 25
	v_readlane_b32 s21, v254, 26
	v_readlane_b32 s22, v254, 27
	v_readlane_b32 s23, v254, 28
	v_readlane_b32 s11, v254, 38
	v_ashrrev_i32_e32 v1, 6, v0
	v_mov_b32_e32 v32, 0xbfb8aa3b
	v_mad_i64_i32 v[8:9], vcc, v1, s64, v[2:3]
	global_load_dword v14, v[4:5], off
	v_mov_b32_e32 v33, 0x3f317217
	v_mov_b32_e32 v34, 0x7f800000
	s_lshr_b32 s3, s10, 6
	s_mul_hi_u32 s7, s3, s64
	s_mul_i32 s6, s3, s64
	s_lshl_b32 s3, s68, 9
	s_mul_i32 s8, s10, 3
.Ldt_main:
	s_add_i32 s9, s3, s8
	s_cmp_lt_i32 s9, 0x210000
	s_cbranch_scc0 .Ldt_tail
	v_lshl_add_u64 v[20:21], v[8:9], 0, s[6:7]
	v_lshl_add_u64 v[26:27], v[6:7], 0, s[12:13]
	global_load_ushort v36, v[8:9], off
	v_lshl_add_u64 v[22:23], v[20:21], 0, s[6:7]
	v_lshl_add_u64 v[28:29], v[26:27], 0, s[12:13]
	global_load_ushort v37, v[20:21], off
	v_lshl_add_u64 v[24:25], v[22:23], 0, s[6:7]
	v_lshl_add_u64 v[30:31], v[28:29], 0, s[12:13]
	global_load_ushort v38, v[22:23], off
	global_load_ushort v39, v[24:25], off
	v_lshl_add_u64 v[8:9], v[24:25], 0, s[6:7]
	s_lshl_b32 s9, s10, 2
	s_add_i32 s3, s3, s9
	s_waitcnt vmcnt(0)
	v_lshlrev_b32_e32 v36, 16, v36
	v_add_f32_e32 v36, v14, v36
	v_mul_f32_e64 v40, |v36|, v32
	v_exp_f32_e32 v40, v40
	v_max_f32_e32 v36, 0, v36
	v_add_f32_e32 v41, 1.0, v40
	v_cmp_gt_f32_e32 vcc, s71, v41
	v_add_f32_e32 v43, -1.0, v41
	v_rcp_f32_e32 v43, v43
	v_cndmask_b32_e64 v42, 0, 32, vcc
	v_ldexp_f32 v42, v41, v42
	v_log_f32_e32 v42, v42
	v_cndmask_b32_e32 v44, 0, v202, vcc
	v_mul_f32_e32 v45, 0x3f317217, v42
	v_fma_f32 v45, v42, v33, -v45
	v_fmac_f32_e32 v45, 0x3377d1cf, v42
	v_fmac_f32_e32 v45, 0x3f317217, v42
	v_cmp_lt_f32_e64 vcc, |v42|, v34
	s_nop 1
	v_cndmask_b32_e32 v42, v42, v45, vcc
	v_sub_f32_e32 v42, v42, v44
	v_mul_f32_e32 v42, v40, v42
	v_mul_f32_e32 v42, v42, v43
	v_cmp_eq_f32_e32 vcc, 1.0, v41
	s_nop 1
	v_cndmask_b32_e32 v40, v42, v40, vcc
	v_add_f32_e32 v36, v36, v40
	v_lshlrev_b32_e32 v37, 16, v37
	v_add_f32_e32 v37, v14, v37
	v_mul_f32_e64 v46, |v37|, v32
	v_exp_f32_e32 v46, v46
	v_max_f32_e32 v37, 0, v37
	v_add_f32_e32 v47, 1.0, v46
	v_cmp_gt_f32_e32 vcc, s71, v47
	v_add_f32_e32 v49, -1.0, v47
	v_rcp_f32_e32 v49, v49
	v_cndmask_b32_e64 v48, 0, 32, vcc
	v_ldexp_f32 v48, v47, v48
	v_log_f32_e32 v48, v48
	v_cndmask_b32_e32 v50, 0, v202, vcc
	v_mul_f32_e32 v51, 0x3f317217, v48
	v_fma_f32 v51, v48, v33, -v51
	v_fmac_f32_e32 v51, 0x3377d1cf, v48
	v_fmac_f32_e32 v51, 0x3f317217, v48
	v_cmp_lt_f32_e64 vcc, |v48|, v34
	s_nop 1
	v_cndmask_b32_e32 v48, v48, v51, vcc
	v_sub_f32_e32 v48, v48, v50
	v_mul_f32_e32 v48, v46, v48
	v_mul_f32_e32 v48, v48, v49
	v_cmp_eq_f32_e32 vcc, 1.0, v47
	s_nop 1
	v_cndmask_b32_e32 v46, v48, v46, vcc
	v_add_f32_e32 v37, v37, v46
	v_lshlrev_b32_e32 v38, 16, v38
	v_add_f32_e32 v38, v14, v38
	v_mul_f32_e64 v52, |v38|, v32
	v_exp_f32_e32 v52, v52
	v_max_f32_e32 v38, 0, v38
	v_add_f32_e32 v53, 1.0, v52
	v_cmp_gt_f32_e32 vcc, s71, v53
	v_add_f32_e32 v55, -1.0, v53
	v_rcp_f32_e32 v55, v55
	v_cndmask_b32_e64 v54, 0, 32, vcc
	v_ldexp_f32 v54, v53, v54
	v_log_f32_e32 v54, v54
	v_cndmask_b32_e32 v56, 0, v202, vcc
	v_mul_f32_e32 v57, 0x3f317217, v54
	v_fma_f32 v57, v54, v33, -v57
	v_fmac_f32_e32 v57, 0x3377d1cf, v54
	v_fmac_f32_e32 v57, 0x3f317217, v54
	v_cmp_lt_f32_e64 vcc, |v54|, v34
	s_nop 1
	v_cndmask_b32_e32 v54, v54, v57, vcc
	v_sub_f32_e32 v54, v54, v56
	v_mul_f32_e32 v54, v52, v54
	v_mul_f32_e32 v54, v54, v55
	v_cmp_eq_f32_e32 vcc, 1.0, v53
	s_nop 1
	v_cndmask_b32_e32 v52, v54, v52, vcc
	v_add_f32_e32 v38, v38, v52
	v_lshlrev_b32_e32 v39, 16, v39
	v_add_f32_e32 v39, v14, v39
	v_mul_f32_e64 v58, |v39|, v32
	v_exp_f32_e32 v58, v58
	v_max_f32_e32 v39, 0, v39
	v_add_f32_e32 v59, 1.0, v58
	v_cmp_gt_f32_e32 vcc, s71, v59
	v_add_f32_e32 v61, -1.0, v59
	v_rcp_f32_e32 v61, v61
	v_cndmask_b32_e64 v60, 0, 32, vcc
	v_ldexp_f32 v60, v59, v60
	v_log_f32_e32 v60, v60
	v_cndmask_b32_e32 v62, 0, v202, vcc
	v_mul_f32_e32 v63, 0x3f317217, v60
	v_fma_f32 v63, v60, v33, -v63
	v_fmac_f32_e32 v63, 0x3377d1cf, v60
	v_fmac_f32_e32 v63, 0x3f317217, v60
	v_cmp_lt_f32_e64 vcc, |v60|, v34
	s_nop 1
	v_cndmask_b32_e32 v60, v60, v63, vcc
	v_sub_f32_e32 v60, v60, v62
	v_mul_f32_e32 v60, v58, v60
	v_mul_f32_e32 v60, v60, v61
	v_cmp_eq_f32_e32 vcc, 1.0, v59
	s_nop 1
	v_cndmask_b32_e32 v58, v60, v58, vcc
	v_add_f32_e32 v39, v39, v58
	global_store_dword v[6:7], v36, off
	global_store_dword v[26:27], v37, off
	global_store_dword v[28:29], v38, off
	global_store_dword v[30:31], v39, off
	v_lshl_add_u64 v[6:7], v[30:31], 0, s[12:13]
	s_branch .Ldt_main
; #define LAS __attribute__((address_space(3)))
; #define INP(k) inp_(a.in[k])
; __device__ __forceinline__ void mlp_phase(const Args& a, unsigned char* ws, const int bid, int l, LAS unsigned char* lds, int tid, int wave, int lane) {
;     ...
;     if (wfixed && bid < NCH * 16) {
; #pragma unroll
;         for (int i = 0; i < 4; ++i) { const int p = tid + i * 512, r = p >> 4, cp = p & 15; *(LAS u32x4*)(L_W + r * 272 + cp * 16) = *(const u32x4*)(wsb + (size_t)(bid & 15) * 16384 + r * 128 + cp * 8); } }
; __device__ __forceinline__ void phase_C0(const Args& a, unsigned char* ws, const int bid, int l, LAS unsigned char* lds, int tid, int wave, int lane) {
;     ...
;     { const bf16_t* z = (const bf16_t*)(ws + WS_Z); float* DT = (float*)(ws + WS_DT); const float* dtb = INP(11) + l * 64;
;       for (int idx = bid * 512 + tid; idx < T * 64; idx += G * 512) { const int t = idx >> 6, j = idx & 63;
;           const float xr = bf1(z[(size_t)t * ZW + ZC_DT + j]) + dtb[j];
;           const float e = __expf(-fabsf(xr)), u = 1.f + e;
;           const float l1p = (u == 1.f) ? e : __logf(u) * e * __builtin_amdgcn_rcpf(u - 1.f);
;           DT[idx] = fmaxf(xr, 0.f) + l1p; } }
.Ldt_tail:
	s_cmp_lt_i32 s3, 0x210000
	s_cbranch_scc0 .Ldt_done
	global_load_ushort v36, v[8:9], off
	v_lshl_add_u64 v[8:9], v[8:9], 0, s[6:7]
	s_add_i32 s3, s3, s10
	s_waitcnt vmcnt(0)
	v_lshlrev_b32_e32 v36, 16, v36
	v_add_f32_e32 v36, v14, v36
	v_mul_f32_e64 v40, |v36|, v32
	v_exp_f32_e32 v40, v40
	v_max_f32_e32 v36, 0, v36
	v_add_f32_e32 v41, 1.0, v40
	v_cmp_gt_f32_e32 vcc, s71, v41
	v_add_f32_e32 v43, -1.0, v41
	v_rcp_f32_e32 v43, v43
	v_cndmask_b32_e64 v42, 0, 32, vcc
	v_ldexp_f32 v42, v41, v42
	v_log_f32_e32 v42, v42
	v_cndmask_b32_e32 v44, 0, v202, vcc
	v_mul_f32_e32 v45, 0x3f317217, v42
	v_fma_f32 v45, v42, v33, -v45
	v_fmac_f32_e32 v45, 0x3377d1cf, v42
	v_fmac_f32_e32 v45, 0x3f317217, v42
	v_cmp_lt_f32_e64 vcc, |v42|, v34
	s_nop 1
	v_cndmask_b32_e32 v42, v42, v45, vcc
	v_sub_f32_e32 v42, v42, v44
	v_mul_f32_e32 v42, v40, v42
	v_mul_f32_e32 v42, v42, v43
	v_cmp_eq_f32_e32 vcc, 1.0, v41
	s_nop 1
	v_cndmask_b32_e32 v40, v42, v40, vcc
	v_add_f32_e32 v36, v36, v40
	global_store_dword v[6:7], v36, off
	v_lshl_add_u64 v[6:7], v[6:7], 0, s[12:13]
	s_branch .Ldt_tail
.Ldt_done:
.LBB0_133:
	s_or_b64 exec, exec, s[4:5]
	s_ashr_i32 s83, s82, 31
	s_lshl_b64 s[4:5], s[82:83], 19
	v_readlane_b32 s6, v254, 47
	v_readlane_b32 s7, v254, 48
	s_add_u32 s3, s6, s4
	s_addc_u32 s4, s7, s5
	s_add_u32 s6, s3, 0x7c000
	s_addc_u32 s7, s4, 0
	s_cmpk_lt_i32 s68, 0x1080
	v_readlane_b32 s10, v253, 19
	s_waitcnt lgkmcnt(0)
	v_and_b32_e32 v41, 15, v164
	s_cselect_b64 s[8:9], -1, 0
	s_cmpk_gt_i32 s68, 0x107f
	v_readlane_b32 s11, v253, 20
	s_cselect_b64 s[4:5], -1, 0
	s_and_b64 s[10:11], s[10:11], s[8:9]
	v_lshlrev_b32_e32 v42, 4, v41
	v_ashrrev_i32_e32 v81, 4, v164
	v_add_u32_e32 v0, 0x200, v164
	v_add_u32_e32 v1, 0x400, v164
	v_add_u32_e32 v2, 0x600, v164
	s_mov_b64 s[16:17], 0
	s_mov_b64 s[14:15], 0
	s_andn2_b64 vcc, exec, s[10:11]
	v_add_u32_e32 v40, 0, v42
	v_lshlrev_b32_e32 v72, 7, v81
	v_ashrrev_i32_e32 v98, 4, v0
	v_ashrrev_i32_e32 v99, 4, v1
	v_ashrrev_i32_e32 v100, 4, v2
	s_cbranch_vccnz .LBB0_135
	s_lshl_b32 s3, s68, 15
	s_and_b32 s3, s3, 0x78000
	s_add_u32 s10, s6, s3
	s_addc_u32 s11, s7, 0
	v_mov_b32_e32 v43, v161
	s_waitcnt vmcnt(10)
	v_lshl_add_u64 v[4:5], s[10:11], 0, v[42:43]
	v_ashrrev_i32_e32 v73, 31, v72
	v_lshl_add_u64 v[0:1], v[72:73], 1, v[4:5]
	global_load_dwordx4 v[0:3], v[0:1], off
	s_movk_i32 s3, 0x110
	v_mad_u64_u32 v[6:7], s[10:11], v81, s3, v[40:41]
	s_waitcnt vmcnt(0)
	ds_write_b128 v6, v[0:3]
	v_lshlrev_b32_e32 v0, 7, v98
	v_ashrrev_i32_e32 v1, 31, v0
	v_lshl_add_u64 v[0:1], v[0:1], 1, v[4:5]
	global_load_dwordx4 v[0:3], v[0:1], off
	v_mad_u64_u32 v[6:7], s[10:11], v98, s3, v[40:41]
	s_waitcnt vmcnt(0)
	ds_write_b128 v6, v[0:3]
	v_lshlrev_b32_e32 v0, 7, v99
	v_ashrrev_i32_e32 v1, 31, v0
	v_lshl_add_u64 v[0:1], v[0:1], 1, v[4:5]
	global_load_dwordx4 v[0:3], v[0:1], off
	v_mad_u64_u32 v[6:7], s[10:11], v99, s3, v[40:41]
	s_waitcnt vmcnt(0)
	ds_write_b128 v6, v[0:3]
	v_lshlrev_b32_e32 v0, 7, v100
	v_ashrrev_i32_e32 v1, 31, v0
	v_lshl_add_u64 v[0:1], v[0:1], 1, v[4:5]
	global_load_dwordx4 v[0:3], v[0:1], off
	v_mad_u64_u32 v[4:5], s[10:11], v100, s3, v[40:41]
	s_waitcnt vmcnt(0)
	ds_write_b128 v4, v[0:3]
